# GEMM K-loops: MFMAs reordered so each accumulator's two k-step MFMAs issue back to back (m-major), on top of attention/S5 load de-serialisation
# speedup vs baseline: 1.0142x; 1.0142x over previous
; #define PG8_STAGE(bufoff, gbase, voff) do { _Pragma("unroll") for (int _i = 0; _i < 2; ++_i) \
;         __builtin_amdgcn_global_load_lds((const unsigned*)((const char*)(gbase) + (voff)[_i]), (LAS unsigned*)(lds + (bufoff) + ldsw + _i * 8192), 16, 0, 0); } while (0)
; #define PG8_LDA(dst, off) do { _Pragma("unroll") for (int m = 0; m < 4; ++m) _Pragma("unroll") for (int k = 0; k < 2; ++k) dst[m][k] = *(const LAS bf16x8*)(lds + (off) + aoff + m * 2048 + k * 1024); } while (0)
; #define PG8_LDB(dst, b, h) do { _Pragma("unroll") for (int n = 0; n < 2; ++n) _Pragma("unroll") for (int k = 0; k < 2; ++k) dst[n][k] = *(const LAS bf16x8*)(lds + PG8_SB(b, h) + boff + n * 2048 + k * 1024); } while (0)
; #define PG8_MMA(ai, bj, At, Bt) do { __builtin_amdgcn_s_setprio(1); _Pragma("unroll") for (int m = 0; m < 4; ++m) _Pragma("unroll") for (int n = 0; n < 2; ++n) _Pragma("unroll") for (int k = 0; k < 2; ++k) \
;         acc[ai][bj][m][n] = __builtin_amdgcn_mfma_f32_16x16x32_bf16(Bt[n][k], At[m][k], acc[ai][bj][m][n], 0, 0, 0); __builtin_amdgcn_s_setprio(0); } while (0)
; #define PG8_WAIT_V(n) asm volatile("s_waitcnt vmcnt(" #n ")" ::: "memory")
; #define PG8_WAIT_L(n) asm volatile("s_waitcnt lgkmcnt(" #n ")" ::: "memory")
; #define PG8_BAR __builtin_amdgcn_s_barrier()
; #define PG8_SCHED __builtin_amdgcn_sched_barrier(0)
; template <class Epi, bool ALIGN_EPI = true>
; __device__ __forceinline__ void gemm_phase(LAS unsigned char* lds, const Gemm g, const StaticOrder& S, const Epi& E) {
;     ...
;             const bool last = (t == nt - 2);
;             const char* a1 = cA + (size_t)(t + 1) * kstep;
;             const char* a2 = last ? nA : cA + (size_t)(t + 2) * kstep; const char* b2 = last ? nB : cB + (size_t)(t + 2) * kstep;
;             const char* a3 = a2 + kstep; const char* b3 = b2 + kstep;
;             PG8_LDB(B0, 0, 0); PG8_LDB(B1, 0, 1); PG8_SCHED; PG8_LDA(At, o0); PG8_STAGE(PG8_SA1(1), a1 + hstep, voffA); PG8_STAGE(o2, a2, voffA);
;             PG8_WAIT_V(10); PG8_WAIT_L(0); PG8_BAR; PG8_MMA(0, 0, At, B0); PG8_MMA(0, 1, At, B1); PG8_BAR; PG8_SCHED;
;             PG8_LDA(At, PG8_SA1(0)); PG8_STAGE(PG8_SB(0, 0), b2, voffB); PG8_STAGE(PG8_SB(0, 1), b2 + hstep, voffB);
;             PG8_WAIT_V(8); PG8_WAIT_L(0); PG8_BAR; PG8_MMA(1, 0, At, B0); PG8_MMA(1, 1, At, B1); PG8_BAR; PG8_SCHED;
.LBB0_221:
	ds_read_b128 v[146:149], v159 offset:32768
	ds_read_b128 v[150:153], v159 offset:33792
	ds_read_b128 v[162:165], v159 offset:34816
	ds_read_b128 v[166:169], v159 offset:35840
	ds_read_b128 v[170:173], v159 offset:49152
	ds_read_b128 v[174:177], v159 offset:50176
	ds_read_b128 v[178:181], v159 offset:51200
	ds_read_b128 v[182:185], v159 offset:52224
	s_mov_b32 s67, s66
	s_mov_b32 s66, s63
	s_mov_b32 s63, s12
	s_add_u32 s12, s10, 0xfff00080
	s_addc_u32 s13, s11, -1
	s_cmp_eq_u32 s69, 60
	s_cselect_b32 s44, s9, s12
	s_cselect_b32 s12, s33, s39
	s_cselect_b32 s45, s5, s13
	s_cselect_b32 s13, s29, s68
	v_add_u32_e32 v154, s63, v157
	ds_read_b128 v[186:189], v154
	ds_read_b128 v[190:193], v154 offset:1024
	ds_read_b128 v[194:197], v154 offset:2048
	ds_read_b128 v[198:201], v154 offset:3072
	ds_read_b128 v[202:205], v154 offset:4096
	ds_read_b128 v[206:209], v154 offset:5120
	ds_read_b128 v[210:213], v154 offset:6144
	ds_read_b128 v[214:217], v154 offset:7168
	v_lshl_add_u64 v[154:155], s[10:11], 0, v[138:139]
	s_add_i32 m0, s46, 0x4000
	s_add_i32 s70, s46, s67
	global_load_lds_dwordx4 v[154:155], off
	v_lshl_add_u64 v[154:155], s[10:11], 0, v[140:141]
	s_add_i32 m0, s46, 0x6000
	v_lshl_add_u64 v[218:219], s[44:45], 0, v[134:135]
	global_load_lds_dwordx4 v[154:155], off
	v_lshl_add_u64 v[154:155], s[44:45], 0, v[130:131]
	s_mov_b32 m0, s70
	s_nop 0
	global_load_lds_dwordx4 v[154:155], off
	s_add_i32 m0, s70, 0x2000
	s_nop 0
	global_load_lds_dwordx4 v[218:219], off
	s_waitcnt vmcnt(10)
	s_waitcnt lgkmcnt(0)
	s_barrier
	s_setprio 1
	s_waitcnt lgkmcnt(0)
	v_mfma_f32_16x16x32_bf16 v[126:129], v[146:149], v[186:189], v[126:129]
	v_mfma_f32_16x16x32_bf16 v[126:129], v[150:153], v[190:193], v[126:129]
	v_mfma_f32_16x16x32_bf16 v[122:125], v[162:165], v[186:189], v[122:125]
	v_mfma_f32_16x16x32_bf16 v[122:125], v[166:169], v[190:193], v[122:125]
	v_mfma_f32_16x16x32_bf16 v[118:121], v[170:173], v[186:189], v[118:121]
	v_mfma_f32_16x16x32_bf16 v[118:121], v[174:177], v[190:193], v[118:121]
	v_mfma_f32_16x16x32_bf16 v[114:117], v[178:181], v[186:189], v[114:117]
	v_mfma_f32_16x16x32_bf16 v[114:117], v[182:185], v[190:193], v[114:117]
	v_mfma_f32_16x16x32_bf16 v[110:113], v[146:149], v[194:197], v[110:113]
	v_mfma_f32_16x16x32_bf16 v[110:113], v[150:153], v[198:201], v[110:113]
	v_mfma_f32_16x16x32_bf16 v[106:109], v[162:165], v[194:197], v[106:109]
	v_mfma_f32_16x16x32_bf16 v[106:109], v[166:169], v[198:201], v[106:109]
	v_mfma_f32_16x16x32_bf16 v[102:105], v[170:173], v[194:197], v[102:105]
	v_mfma_f32_16x16x32_bf16 v[102:105], v[174:177], v[198:201], v[102:105]
	v_mfma_f32_16x16x32_bf16 v[98:101], v[178:181], v[194:197], v[98:101]
	v_mfma_f32_16x16x32_bf16 v[98:101], v[182:185], v[198:201], v[98:101]
	s_setprio 0
	s_setprio 1
	v_mfma_f32_16x16x32_bf16 v[94:97], v[146:149], v[202:205], v[94:97]
	v_mfma_f32_16x16x32_bf16 v[94:97], v[150:153], v[206:209], v[94:97]
	v_mfma_f32_16x16x32_bf16 v[90:93], v[162:165], v[202:205], v[90:93]
	v_mfma_f32_16x16x32_bf16 v[90:93], v[166:169], v[206:209], v[90:93]
	v_mfma_f32_16x16x32_bf16 v[86:89], v[170:173], v[202:205], v[86:89]
	v_mfma_f32_16x16x32_bf16 v[86:89], v[174:177], v[206:209], v[86:89]
	v_mfma_f32_16x16x32_bf16 v[82:85], v[178:181], v[202:205], v[82:85]
	v_mfma_f32_16x16x32_bf16 v[82:85], v[182:185], v[206:209], v[82:85]
	v_mfma_f32_16x16x32_bf16 v[78:81], v[146:149], v[210:213], v[78:81]
	v_mfma_f32_16x16x32_bf16 v[78:81], v[150:153], v[214:217], v[78:81]
	v_mfma_f32_16x16x32_bf16 v[74:77], v[162:165], v[210:213], v[74:77]
	v_mfma_f32_16x16x32_bf16 v[74:77], v[166:169], v[214:217], v[74:77]
	v_mfma_f32_16x16x32_bf16 v[70:73], v[170:173], v[210:213], v[70:73]
	v_mfma_f32_16x16x32_bf16 v[70:73], v[174:177], v[214:217], v[70:73]
	v_mfma_f32_16x16x32_bf16 v[66:69], v[178:181], v[210:213], v[66:69]
	v_mfma_f32_16x16x32_bf16 v[66:69], v[182:185], v[214:217], v[66:69]
	s_setprio 0
	s_barrier
	s_mov_b32 m0, s47
	v_lshl_add_u64 v[220:221], s[12:13], 0, v[132:133]
	s_add_u32 s70, s12, 0x100000
	ds_read_b128 v[186:189], v157
	ds_read_b128 v[190:193], v157 offset:1024
	ds_read_b128 v[194:197], v157 offset:2048
	ds_read_b128 v[198:201], v157 offset:3072
	ds_read_b128 v[202:205], v157 offset:4096
	ds_read_b128 v[206:209], v157 offset:5120
	ds_read_b128 v[210:213], v157 offset:6144
	ds_read_b128 v[214:217], v157 offset:7168
	global_load_lds_dwordx4 v[220:221], off
	v_lshl_add_u64 v[222:223], s[12:13], 0, v[136:137]
	s_mov_b32 m0, s58
	s_addc_u32 s71, s13, 0
	global_load_lds_dwordx4 v[222:223], off
	v_lshl_add_u64 v[224:225], s[70:71], 0, v[132:133]
	s_mov_b32 m0, s59
	s_nop 0
	global_load_lds_dwordx4 v[224:225], off
	v_lshl_add_u64 v[224:225], s[70:71], 0, v[136:137]
	s_mov_b32 m0, s60
	s_nop 0
	global_load_lds_dwordx4 v[224:225], off
	s_waitcnt vmcnt(8)
	s_waitcnt lgkmcnt(0)
	s_barrier
; #define PG8_STAGE(bufoff, gbase, voff) do { _Pragma("unroll") for (int _i = 0; _i < 2; ++_i) \
;         __builtin_amdgcn_global_load_lds((const unsigned*)((const char*)(gbase) + (voff)[_i]), (LAS unsigned*)(lds + (bufoff) + ldsw + _i * 8192), 16, 0, 0); } while (0)
; #define PG8_LDA(dst, off) do { _Pragma("unroll") for (int m = 0; m < 4; ++m) _Pragma("unroll") for (int k = 0; k < 2; ++k) dst[m][k] = *(const LAS bf16x8*)(lds + (off) + aoff + m * 2048 + k * 1024); } while (0)
; #define PG8_LDB(dst, b, h) do { _Pragma("unroll") for (int n = 0; n < 2; ++n) _Pragma("unroll") for (int k = 0; k < 2; ++k) dst[n][k] = *(const LAS bf16x8*)(lds + PG8_SB(b, h) + boff + n * 2048 + k * 1024); } while (0)
; #define PG8_MMA(ai, bj, At, Bt) do { __builtin_amdgcn_s_setprio(1); _Pragma("unroll") for (int m = 0; m < 4; ++m) _Pragma("unroll") for (int n = 0; n < 2; ++n) _Pragma("unroll") for (int k = 0; k < 2; ++k) \
;         acc[ai][bj][m][n] = __builtin_amdgcn_mfma_f32_16x16x32_bf16(Bt[n][k], At[m][k], acc[ai][bj][m][n], 0, 0, 0); __builtin_amdgcn_s_setprio(0); } while (0)
; #define PG8_WAIT_V(n) asm volatile("s_waitcnt vmcnt(" #n ")" ::: "memory")
; #define PG8_WAIT_L(n) asm volatile("s_waitcnt lgkmcnt(" #n ")" ::: "memory")
; #define PG8_BAR __builtin_amdgcn_s_barrier()
; #define PG8_SCHED __builtin_amdgcn_sched_barrier(0)
; template <class Epi, bool ALIGN_EPI = true>
; __device__ __forceinline__ void gemm_phase(LAS unsigned char* lds, const Gemm g, const StaticOrder& S, const Epi& E) {
;     ...
;             PG8_WAIT_V(8); PG8_WAIT_L(0); PG8_BAR; PG8_MMA(1, 0, At, B0); PG8_MMA(1, 1, At, B1); PG8_BAR; PG8_SCHED;
;             PG8_LDB(B0, 1, 0); PG8_LDB(B1, 1, 1); PG8_SCHED; PG8_LDA(At, o1); PG8_STAGE(PG8_SA1(0), a2 + hstep, voffA); PG8_STAGE(o0, a3, voffA);
;             PG8_WAIT_V(10); PG8_WAIT_L(0); PG8_BAR; PG8_MMA(0, 0, At, B0); PG8_MMA(0, 1, At, B1); PG8_BAR; PG8_SCHED;
	s_setprio 1
	s_waitcnt lgkmcnt(0)
	v_mfma_f32_16x16x32_bf16 v[62:65], v[146:149], v[186:189], v[62:65]
	v_mfma_f32_16x16x32_bf16 v[62:65], v[150:153], v[190:193], v[62:65]
	v_mfma_f32_16x16x32_bf16 v[58:61], v[162:165], v[186:189], v[58:61]
	v_mfma_f32_16x16x32_bf16 v[58:61], v[166:169], v[190:193], v[58:61]
	v_mfma_f32_16x16x32_bf16 v[54:57], v[170:173], v[186:189], v[54:57]
	v_mfma_f32_16x16x32_bf16 v[54:57], v[174:177], v[190:193], v[54:57]
	v_mfma_f32_16x16x32_bf16 v[50:53], v[178:181], v[186:189], v[50:53]
	v_mfma_f32_16x16x32_bf16 v[50:53], v[182:185], v[190:193], v[50:53]
	v_mfma_f32_16x16x32_bf16 v[46:49], v[146:149], v[194:197], v[46:49]
	v_mfma_f32_16x16x32_bf16 v[46:49], v[150:153], v[198:201], v[46:49]
	v_mfma_f32_16x16x32_bf16 v[42:45], v[162:165], v[194:197], v[42:45]
	v_mfma_f32_16x16x32_bf16 v[42:45], v[166:169], v[198:201], v[42:45]
	v_mfma_f32_16x16x32_bf16 v[38:41], v[170:173], v[194:197], v[38:41]
	v_mfma_f32_16x16x32_bf16 v[38:41], v[174:177], v[198:201], v[38:41]
	v_mfma_f32_16x16x32_bf16 v[34:37], v[178:181], v[194:197], v[34:37]
	v_mfma_f32_16x16x32_bf16 v[34:37], v[182:185], v[198:201], v[34:37]
	s_setprio 0
	s_setprio 1
	v_mfma_f32_16x16x32_bf16 v[30:33], v[146:149], v[202:205], v[30:33]
	v_mfma_f32_16x16x32_bf16 v[30:33], v[150:153], v[206:209], v[30:33]
	v_mfma_f32_16x16x32_bf16 v[26:29], v[162:165], v[202:205], v[26:29]
	v_mfma_f32_16x16x32_bf16 v[26:29], v[166:169], v[206:209], v[26:29]
	v_mfma_f32_16x16x32_bf16 v[22:25], v[170:173], v[202:205], v[22:25]
	v_mfma_f32_16x16x32_bf16 v[22:25], v[174:177], v[206:209], v[22:25]
	v_mfma_f32_16x16x32_bf16 v[18:21], v[178:181], v[202:205], v[18:21]
	v_mfma_f32_16x16x32_bf16 v[18:21], v[182:185], v[206:209], v[18:21]
	v_mfma_f32_16x16x32_bf16 v[14:17], v[146:149], v[210:213], v[14:17]
	v_mfma_f32_16x16x32_bf16 v[14:17], v[150:153], v[214:217], v[14:17]
	v_mfma_f32_16x16x32_bf16 v[10:13], v[162:165], v[210:213], v[10:13]
	v_mfma_f32_16x16x32_bf16 v[10:13], v[166:169], v[214:217], v[10:13]
	v_mfma_f32_16x16x32_bf16 v[6:9], v[170:173], v[210:213], v[6:9]
	v_mfma_f32_16x16x32_bf16 v[6:9], v[174:177], v[214:217], v[6:9]
	v_mfma_f32_16x16x32_bf16 v[2:5], v[178:181], v[210:213], v[2:5]
	v_mfma_f32_16x16x32_bf16 v[2:5], v[182:185], v[214:217], v[2:5]
	s_setprio 0
	s_barrier
	s_add_i32 s70, 0, 0x10000
	v_add_u32_e32 v161, s70, v156
	s_add_i32 s71, 0, 0x14000
	ds_read_b128 v[146:149], v161
	ds_read_b128 v[150:153], v161 offset:1024
	ds_read_b128 v[162:165], v161 offset:2048
	ds_read_b128 v[166:169], v161 offset:3072
	v_add_u32_e32 v161, s71, v156
	ds_read_b128 v[170:173], v161
	ds_read_b128 v[174:177], v161 offset:1024
	ds_read_b128 v[178:181], v161 offset:2048
	ds_read_b128 v[182:185], v161 offset:3072
	s_add_u32 s44, s44, 0x100000
	s_addc_u32 s45, s45, 0
	s_mov_b32 m0, s46
	v_add_u32_e32 v161, s66, v157
	v_lshl_add_u64 v[224:225], s[44:45], 0, v[130:131]
	ds_read_b128 v[186:189], v161
	ds_read_b128 v[190:193], v161 offset:1024
	ds_read_b128 v[194:197], v161 offset:2048
	ds_read_b128 v[198:201], v161 offset:3072
	ds_read_b128 v[202:205], v161 offset:4096
	ds_read_b128 v[206:209], v161 offset:5120
	ds_read_b128 v[210:213], v161 offset:6144
	ds_read_b128 v[214:217], v161 offset:7168
	global_load_lds_dwordx4 v[224:225], off
	v_lshl_add_u64 v[224:225], s[44:45], 0, v[134:135]
	s_mov_b32 m0, s61
	s_add_i32 s44, s46, s63
	global_load_lds_dwordx4 v[224:225], off
	v_lshl_add_u64 v[154:155], v[154:155], 0, s[24:25]
	s_mov_b32 m0, s44
	s_nop 0
	global_load_lds_dwordx4 v[154:155], off
	v_lshl_add_u64 v[154:155], v[218:219], 0, s[24:25]
	s_add_i32 m0, s44, 0x2000
	s_nop 0
	global_load_lds_dwordx4 v[154:155], off
	s_waitcnt vmcnt(10)
	s_waitcnt lgkmcnt(0)
	s_barrier
; #define PG8_STAGE(bufoff, gbase, voff) do { _Pragma("unroll") for (int _i = 0; _i < 2; ++_i) \
;         __builtin_amdgcn_global_load_lds((const unsigned*)((const char*)(gbase) + (voff)[_i]), (LAS unsigned*)(lds + (bufoff) + ldsw + _i * 8192), 16, 0, 0); } while (0)
; #define PG8_LDA(dst, off) do { _Pragma("unroll") for (int m = 0; m < 4; ++m) _Pragma("unroll") for (int k = 0; k < 2; ++k) dst[m][k] = *(const LAS bf16x8*)(lds + (off) + aoff + m * 2048 + k * 1024); } while (0)
; #define PG8_MMA(ai, bj, At, Bt) do { __builtin_amdgcn_s_setprio(1); _Pragma("unroll") for (int m = 0; m < 4; ++m) _Pragma("unroll") for (int n = 0; n < 2; ++n) _Pragma("unroll") for (int k = 0; k < 2; ++k) \
;         acc[ai][bj][m][n] = __builtin_amdgcn_mfma_f32_16x16x32_bf16(Bt[n][k], At[m][k], acc[ai][bj][m][n], 0, 0, 0); __builtin_amdgcn_s_setprio(0); } while (0)
; #define PG8_WAIT_V(n) asm volatile("s_waitcnt vmcnt(" #n ")" ::: "memory")
; #define PG8_WAIT_L(n) asm volatile("s_waitcnt lgkmcnt(" #n ")" ::: "memory")
; #define PG8_BAR __builtin_amdgcn_s_barrier()
; #define PG8_SCHED __builtin_amdgcn_sched_barrier(0)
; template <class Epi, bool ALIGN_EPI = true>
; __device__ __forceinline__ void gemm_phase(LAS unsigned char* lds, const Gemm g, const StaticOrder& S, const Epi& E) {
;     ...
;             PG8_WAIT_V(10); PG8_WAIT_L(0); PG8_BAR; PG8_MMA(0, 0, At, B0); PG8_MMA(0, 1, At, B1); PG8_BAR; PG8_SCHED;
;             PG8_LDA(At, PG8_SA1(1)); PG8_STAGE(PG8_SB(1, 0), b3, voffB); PG8_STAGE(PG8_SB(1, 1), b3 + hstep, voffB);
;             PG8_WAIT_V(8); PG8_WAIT_L(0); PG8_BAR; PG8_MMA(1, 0, At, B0); PG8_MMA(1, 1, At, B1); PG8_BAR; PG8_SCHED;
;             { const int t_ = o0; o0 = o2; o2 = o1; o1 = t_; }
;         }
;         if constexpr (ALIGN_EPI) { if (wr == 0) PG8_BAR; }
	s_setprio 1
	s_waitcnt lgkmcnt(0)
	v_mfma_f32_16x16x32_bf16 v[126:129], v[146:149], v[186:189], v[126:129]
	v_mfma_f32_16x16x32_bf16 v[126:129], v[150:153], v[190:193], v[126:129]
	v_mfma_f32_16x16x32_bf16 v[122:125], v[162:165], v[186:189], v[122:125]
	v_mfma_f32_16x16x32_bf16 v[122:125], v[166:169], v[190:193], v[122:125]
	v_mfma_f32_16x16x32_bf16 v[118:121], v[170:173], v[186:189], v[118:121]
	v_mfma_f32_16x16x32_bf16 v[118:121], v[174:177], v[190:193], v[118:121]
	v_mfma_f32_16x16x32_bf16 v[114:117], v[178:181], v[186:189], v[114:117]
	v_mfma_f32_16x16x32_bf16 v[114:117], v[182:185], v[190:193], v[114:117]
	v_mfma_f32_16x16x32_bf16 v[110:113], v[146:149], v[194:197], v[110:113]
	v_mfma_f32_16x16x32_bf16 v[110:113], v[150:153], v[198:201], v[110:113]
	v_mfma_f32_16x16x32_bf16 v[106:109], v[162:165], v[194:197], v[106:109]
	v_mfma_f32_16x16x32_bf16 v[106:109], v[166:169], v[198:201], v[106:109]
	v_mfma_f32_16x16x32_bf16 v[102:105], v[170:173], v[194:197], v[102:105]
	v_mfma_f32_16x16x32_bf16 v[102:105], v[174:177], v[198:201], v[102:105]
	v_mfma_f32_16x16x32_bf16 v[98:101], v[178:181], v[194:197], v[98:101]
	v_mfma_f32_16x16x32_bf16 v[98:101], v[182:185], v[198:201], v[98:101]
	s_setprio 0
	s_setprio 1
	v_mfma_f32_16x16x32_bf16 v[94:97], v[146:149], v[202:205], v[94:97]
	v_mfma_f32_16x16x32_bf16 v[94:97], v[150:153], v[206:209], v[94:97]
	v_mfma_f32_16x16x32_bf16 v[90:93], v[162:165], v[202:205], v[90:93]
	v_mfma_f32_16x16x32_bf16 v[90:93], v[166:169], v[206:209], v[90:93]
	v_mfma_f32_16x16x32_bf16 v[86:89], v[170:173], v[202:205], v[86:89]
	v_mfma_f32_16x16x32_bf16 v[86:89], v[174:177], v[206:209], v[86:89]
	v_mfma_f32_16x16x32_bf16 v[82:85], v[178:181], v[202:205], v[82:85]
	v_mfma_f32_16x16x32_bf16 v[82:85], v[182:185], v[206:209], v[82:85]
	v_mfma_f32_16x16x32_bf16 v[78:81], v[146:149], v[210:213], v[78:81]
	v_mfma_f32_16x16x32_bf16 v[78:81], v[150:153], v[214:217], v[78:81]
	v_mfma_f32_16x16x32_bf16 v[74:77], v[162:165], v[210:213], v[74:77]
	v_mfma_f32_16x16x32_bf16 v[74:77], v[166:169], v[214:217], v[74:77]
	v_mfma_f32_16x16x32_bf16 v[70:73], v[170:173], v[210:213], v[70:73]
	v_mfma_f32_16x16x32_bf16 v[70:73], v[174:177], v[214:217], v[70:73]
	v_mfma_f32_16x16x32_bf16 v[66:69], v[178:181], v[210:213], v[66:69]
	v_mfma_f32_16x16x32_bf16 v[66:69], v[182:185], v[214:217], v[66:69]
	s_setprio 0
	s_barrier
	s_add_i32 s44, s70, s35
	v_lshl_add_u64 v[154:155], v[220:221], 0, s[24:25]
	s_mov_b32 m0, s44
	ds_read_b128 v[186:189], v157 offset:16384
	ds_read_b128 v[190:193], v157 offset:17408
	ds_read_b128 v[194:197], v157 offset:18432
	ds_read_b128 v[198:201], v157 offset:19456
	ds_read_b128 v[202:205], v157 offset:20480
	ds_read_b128 v[206:209], v157 offset:21504
	ds_read_b128 v[210:213], v157 offset:22528
	ds_read_b128 v[214:217], v157 offset:23552
	global_load_lds_dwordx4 v[154:155], off
	s_add_i32 m0, s44, 0x2000
	s_add_u32 s12, s12, 0x100080
	v_lshl_add_u64 v[154:155], v[222:223], 0, s[24:25]
	s_addc_u32 s13, s13, 0
	s_add_i32 s44, s71, s35
	global_load_lds_dwordx4 v[154:155], off
	v_lshl_add_u64 v[154:155], s[12:13], 0, v[132:133]
	s_mov_b32 m0, s44
	s_nop 0
	global_load_lds_dwordx4 v[154:155], off
	v_lshl_add_u64 v[154:155], s[12:13], 0, v[136:137]
	s_add_i32 m0, s44, 0x2000
	s_nop 0
	global_load_lds_dwordx4 v[154:155], off
	s_waitcnt vmcnt(8)
	s_waitcnt lgkmcnt(0)
	s_barrier
	s_setprio 1
	s_waitcnt lgkmcnt(0)
	v_mfma_f32_16x16x32_bf16 v[62:65], v[146:149], v[186:189], v[62:65]
	v_mfma_f32_16x16x32_bf16 v[62:65], v[150:153], v[190:193], v[62:65]
	v_mfma_f32_16x16x32_bf16 v[58:61], v[162:165], v[186:189], v[58:61]
	v_mfma_f32_16x16x32_bf16 v[58:61], v[166:169], v[190:193], v[58:61]
	v_mfma_f32_16x16x32_bf16 v[54:57], v[170:173], v[186:189], v[54:57]
	v_mfma_f32_16x16x32_bf16 v[54:57], v[174:177], v[190:193], v[54:57]
	v_mfma_f32_16x16x32_bf16 v[50:53], v[178:181], v[186:189], v[50:53]
	v_mfma_f32_16x16x32_bf16 v[50:53], v[182:185], v[190:193], v[50:53]
	v_mfma_f32_16x16x32_bf16 v[46:49], v[146:149], v[194:197], v[46:49]
	v_mfma_f32_16x16x32_bf16 v[46:49], v[150:153], v[198:201], v[46:49]
	v_mfma_f32_16x16x32_bf16 v[42:45], v[162:165], v[194:197], v[42:45]
	v_mfma_f32_16x16x32_bf16 v[42:45], v[166:169], v[198:201], v[42:45]
	v_mfma_f32_16x16x32_bf16 v[38:41], v[170:173], v[194:197], v[38:41]
	v_mfma_f32_16x16x32_bf16 v[38:41], v[174:177], v[198:201], v[38:41]
	v_mfma_f32_16x16x32_bf16 v[34:37], v[178:181], v[194:197], v[34:37]
	v_mfma_f32_16x16x32_bf16 v[34:37], v[182:185], v[198:201], v[34:37]
	s_setprio 0
	s_setprio 1
	v_mfma_f32_16x16x32_bf16 v[30:33], v[146:149], v[202:205], v[30:33]
	v_mfma_f32_16x16x32_bf16 v[30:33], v[150:153], v[206:209], v[30:33]
	v_mfma_f32_16x16x32_bf16 v[26:29], v[162:165], v[202:205], v[26:29]
	v_mfma_f32_16x16x32_bf16 v[26:29], v[166:169], v[206:209], v[26:29]
	v_mfma_f32_16x16x32_bf16 v[22:25], v[170:173], v[202:205], v[22:25]
	v_mfma_f32_16x16x32_bf16 v[22:25], v[174:177], v[206:209], v[22:25]
	v_mfma_f32_16x16x32_bf16 v[18:21], v[178:181], v[202:205], v[18:21]
	v_mfma_f32_16x16x32_bf16 v[18:21], v[182:185], v[206:209], v[18:21]
	v_mfma_f32_16x16x32_bf16 v[14:17], v[146:149], v[210:213], v[14:17]
	v_mfma_f32_16x16x32_bf16 v[14:17], v[150:153], v[214:217], v[14:17]
	v_mfma_f32_16x16x32_bf16 v[10:13], v[162:165], v[210:213], v[10:13]
	v_mfma_f32_16x16x32_bf16 v[10:13], v[166:169], v[214:217], v[10:13]
	v_mfma_f32_16x16x32_bf16 v[6:9], v[170:173], v[210:213], v[6:9]
	v_mfma_f32_16x16x32_bf16 v[6:9], v[174:177], v[214:217], v[6:9]
	v_mfma_f32_16x16x32_bf16 v[2:5], v[178:181], v[210:213], v[2:5]
	v_mfma_f32_16x16x32_bf16 v[2:5], v[182:185], v[214:217], v[2:5]
	s_setprio 0
	s_barrier
	s_add_i32 s69, s69, 2
	s_add_u32 s10, s10, 0x100
	s_addc_u32 s11, s11, 0
	s_add_u32 s39, s39, 0x100
	s_addc_u32 s68, s68, 0
	s_cmp_gt_u32 s69, 61
	s_mov_b32 s12, s67
	s_cbranch_scc0 .LBB0_221
	s_and_b64 vcc, exec, s[26:27]
	s_cbranch_vccz .LBB0_224
	s_barrier

; #define PG8_STAGE(bufoff, gbase, voff) do { _Pragma("unroll") for (int _i = 0; _i < 2; ++_i) \
;         __builtin_amdgcn_global_load_lds((const unsigned*)((const char*)(gbase) + (voff)[_i]), (LAS unsigned*)(lds + (bufoff) + ldsw + _i * 8192), 16, 0, 0); } while (0)
; #define PG8_LDA(dst, off) do { _Pragma("unroll") for (int m = 0; m < 4; ++m) _Pragma("unroll") for (int k = 0; k < 2; ++k) dst[m][k] = *(const LAS bf16x8*)(lds + (off) + aoff + m * 2048 + k * 1024); } while (0)
; #define PG8_LDB(dst, b, h) do { _Pragma("unroll") for (int n = 0; n < 2; ++n) _Pragma("unroll") for (int k = 0; k < 2; ++k) dst[n][k] = *(const LAS bf16x8*)(lds + PG8_SB(b, h) + boff + n * 2048 + k * 1024); } while (0)
; #define PG8_MMA(ai, bj, At, Bt) do { __builtin_amdgcn_s_setprio(1); _Pragma("unroll") for (int m = 0; m < 4; ++m) _Pragma("unroll") for (int n = 0; n < 2; ++n) _Pragma("unroll") for (int k = 0; k < 2; ++k) \
;         acc[ai][bj][m][n] = __builtin_amdgcn_mfma_f32_16x16x32_bf16(Bt[n][k], At[m][k], acc[ai][bj][m][n], 0, 0, 0); __builtin_amdgcn_s_setprio(0); } while (0)
; #define PG8_WAIT_V(n) asm volatile("s_waitcnt vmcnt(" #n ")" ::: "memory")
; #define PG8_WAIT_L(n) asm volatile("s_waitcnt lgkmcnt(" #n ")" ::: "memory")
; #define PG8_BAR __builtin_amdgcn_s_barrier()
; #define PG8_SCHED __builtin_amdgcn_sched_barrier(0)
; template <class Epi, bool ALIGN_EPI = true>
; __device__ __forceinline__ void gemm_phase(LAS unsigned char* lds, const Gemm g, const StaticOrder& S, const Epi& E) {
;     ...
;             const bool last = (t == nt - 2);
;             const char* a1 = cA + (size_t)(t + 1) * kstep;
;             const char* a2 = last ? nA : cA + (size_t)(t + 2) * kstep; const char* b2 = last ? nB : cB + (size_t)(t + 2) * kstep;
;             const char* a3 = a2 + kstep; const char* b3 = b2 + kstep;
;             PG8_LDB(B0, 0, 0); PG8_LDB(B1, 0, 1); PG8_SCHED; PG8_LDA(At, o0); PG8_STAGE(PG8_SA1(1), a1 + hstep, voffA); PG8_STAGE(o2, a2, voffA);
;             PG8_WAIT_V(10); PG8_WAIT_L(0); PG8_BAR; PG8_MMA(0, 0, At, B0); PG8_MMA(0, 1, At, B1); PG8_BAR; PG8_SCHED;
;             PG8_LDA(At, PG8_SA1(0)); PG8_STAGE(PG8_SB(0, 0), b2, voffB); PG8_STAGE(PG8_SB(0, 1), b2 + hstep, voffB);
;             PG8_WAIT_V(8); PG8_WAIT_L(0); PG8_BAR; PG8_MMA(1, 0, At, B0); PG8_MMA(1, 1, At, B1); PG8_BAR; PG8_SCHED;
.LBB0_610:
	ds_read_b128 v[98:101], v209 offset:32768
	ds_read_b128 v[110:113], v209 offset:33792
	ds_read_b128 v[122:125], v209 offset:34816
	ds_read_b128 v[134:137], v209 offset:35840
	ds_read_b128 v[146:149], v209 offset:49152
	ds_read_b128 v[150:153], v209 offset:50176
	ds_read_b128 v[154:157], v209 offset:51200
	ds_read_b128 v[158:161], v209 offset:52224
	s_mov_b32 s56, s54
	s_mov_b32 s54, s52
	s_mov_b32 s52, s42
	s_add_u32 s42, s40, 0xfff80080
	s_addc_u32 s43, s41, -1
	s_cmp_eq_u32 s62, 28
	s_cselect_b32 s44, s58, s42
	s_cselect_b32 s42, s59, s60
	s_cselect_b32 s45, s25, s43
	s_cselect_b32 s43, s23, s61
	v_add_u32_e32 v210, s52, v207
	v_lshl_add_u64 v[214:215], s[40:41], 0, v[182:183]
	s_add_i32 m0, s39, 0x4000
	ds_read_b128 v[162:165], v210
	ds_read_b128 v[166:169], v210 offset:1024
	ds_read_b128 v[170:173], v210 offset:2048
	ds_read_b128 v[190:193], v210 offset:3072
	ds_read_b128 v[194:197], v210 offset:4096
	ds_read_b128 v[198:201], v210 offset:5120
	ds_read_b128 v[202:205], v210 offset:6144
	ds_read_b128 v[210:213], v210 offset:7168
	global_load_lds_dwordx4 v[214:215], off
	v_lshl_add_u64 v[214:215], s[40:41], 0, v[184:185]
	s_add_i32 m0, s39, 0x6000
	s_add_i32 s63, s39, s56
	global_load_lds_dwordx4 v[214:215], off
	v_lshl_add_u64 v[214:215], s[44:45], 0, v[174:175]
	s_mov_b32 m0, s63
	v_lshl_add_u64 v[216:217], s[44:45], 0, v[178:179]
	global_load_lds_dwordx4 v[214:215], off
	s_add_i32 m0, s63, 0x2000
	s_nop 0
	global_load_lds_dwordx4 v[216:217], off
	s_waitcnt vmcnt(10)
	s_waitcnt lgkmcnt(0)
	s_barrier
	s_setprio 1
	s_waitcnt lgkmcnt(0)
	v_mfma_f32_16x16x32_bf16 v[86:89], v[98:101], v[162:165], v[86:89]
	v_mfma_f32_16x16x32_bf16 v[86:89], v[110:113], v[166:169], v[86:89]
	v_mfma_f32_16x16x32_bf16 v[74:77], v[122:125], v[162:165], v[74:77]
	v_mfma_f32_16x16x32_bf16 v[74:77], v[134:137], v[166:169], v[74:77]
	v_mfma_f32_16x16x32_bf16 v[142:145], v[146:149], v[162:165], v[142:145]
	v_mfma_f32_16x16x32_bf16 v[142:145], v[150:153], v[166:169], v[142:145]
	v_mfma_f32_16x16x32_bf16 v[138:141], v[154:157], v[162:165], v[138:141]
	v_mfma_f32_16x16x32_bf16 v[138:141], v[158:161], v[166:169], v[138:141]
	v_mfma_f32_16x16x32_bf16 v[130:133], v[98:101], v[170:173], v[130:133]
	v_mfma_f32_16x16x32_bf16 v[130:133], v[110:113], v[190:193], v[130:133]
	v_mfma_f32_16x16x32_bf16 v[126:129], v[122:125], v[170:173], v[126:129]
	v_mfma_f32_16x16x32_bf16 v[126:129], v[134:137], v[190:193], v[126:129]
	v_mfma_f32_16x16x32_bf16 v[118:121], v[146:149], v[170:173], v[118:121]
	v_mfma_f32_16x16x32_bf16 v[118:121], v[150:153], v[190:193], v[118:121]
	v_mfma_f32_16x16x32_bf16 v[114:117], v[154:157], v[170:173], v[114:117]
	v_mfma_f32_16x16x32_bf16 v[114:117], v[158:161], v[190:193], v[114:117]
	s_setprio 0
	s_setprio 1
	v_mfma_f32_16x16x32_bf16 v[106:109], v[98:101], v[194:197], v[106:109]
	v_mfma_f32_16x16x32_bf16 v[106:109], v[110:113], v[198:201], v[106:109]
	v_mfma_f32_16x16x32_bf16 v[102:105], v[122:125], v[194:197], v[102:105]
	v_mfma_f32_16x16x32_bf16 v[102:105], v[134:137], v[198:201], v[102:105]
	v_mfma_f32_16x16x32_bf16 v[94:97], v[146:149], v[194:197], v[94:97]
	v_mfma_f32_16x16x32_bf16 v[94:97], v[150:153], v[198:201], v[94:97]
	v_mfma_f32_16x16x32_bf16 v[90:93], v[154:157], v[194:197], v[90:93]
	v_mfma_f32_16x16x32_bf16 v[90:93], v[158:161], v[198:201], v[90:93]
	v_mfma_f32_16x16x32_bf16 v[82:85], v[98:101], v[202:205], v[82:85]
	v_mfma_f32_16x16x32_bf16 v[82:85], v[110:113], v[210:213], v[82:85]
	v_mfma_f32_16x16x32_bf16 v[78:81], v[122:125], v[202:205], v[78:81]
	v_mfma_f32_16x16x32_bf16 v[78:81], v[134:137], v[210:213], v[78:81]
	v_mfma_f32_16x16x32_bf16 v[70:73], v[146:149], v[202:205], v[70:73]
	v_mfma_f32_16x16x32_bf16 v[70:73], v[150:153], v[210:213], v[70:73]
	v_mfma_f32_16x16x32_bf16 v[66:69], v[154:157], v[202:205], v[66:69]
	v_mfma_f32_16x16x32_bf16 v[66:69], v[158:161], v[210:213], v[66:69]
	s_setprio 0
	s_barrier
	s_mov_b32 m0, s46
	v_lshl_add_u64 v[218:219], s[42:43], 0, v[176:177]
	s_add_u32 s64, s42, 0x80000
	ds_read_b128 v[162:165], v207
	ds_read_b128 v[166:169], v207 offset:1024
	ds_read_b128 v[170:173], v207 offset:2048
	ds_read_b128 v[190:193], v207 offset:3072
	ds_read_b128 v[194:197], v207 offset:4096
	ds_read_b128 v[198:201], v207 offset:5120
	ds_read_b128 v[202:205], v207 offset:6144
	ds_read_b128 v[210:213], v207 offset:7168
	global_load_lds_dwordx4 v[218:219], off
	v_lshl_add_u64 v[220:221], s[42:43], 0, v[180:181]
	s_mov_b32 m0, s47
	s_addc_u32 s65, s43, 0
	global_load_lds_dwordx4 v[220:221], off
	v_lshl_add_u64 v[222:223], s[64:65], 0, v[176:177]
	s_mov_b32 m0, s48
	s_nop 0
	global_load_lds_dwordx4 v[222:223], off
	v_lshl_add_u64 v[222:223], s[64:65], 0, v[180:181]
	s_mov_b32 m0, s49
	s_nop 0
	global_load_lds_dwordx4 v[222:223], off
	s_waitcnt vmcnt(8)
	s_waitcnt lgkmcnt(0)
	s_barrier
; #define PG8_STAGE(bufoff, gbase, voff) do { _Pragma("unroll") for (int _i = 0; _i < 2; ++_i) \
;         __builtin_amdgcn_global_load_lds((const unsigned*)((const char*)(gbase) + (voff)[_i]), (LAS unsigned*)(lds + (bufoff) + ldsw + _i * 8192), 16, 0, 0); } while (0)
; #define PG8_LDA(dst, off) do { _Pragma("unroll") for (int m = 0; m < 4; ++m) _Pragma("unroll") for (int k = 0; k < 2; ++k) dst[m][k] = *(const LAS bf16x8*)(lds + (off) + aoff + m * 2048 + k * 1024); } while (0)
; #define PG8_LDB(dst, b, h) do { _Pragma("unroll") for (int n = 0; n < 2; ++n) _Pragma("unroll") for (int k = 0; k < 2; ++k) dst[n][k] = *(const LAS bf16x8*)(lds + PG8_SB(b, h) + boff + n * 2048 + k * 1024); } while (0)
; #define PG8_MMA(ai, bj, At, Bt) do { __builtin_amdgcn_s_setprio(1); _Pragma("unroll") for (int m = 0; m < 4; ++m) _Pragma("unroll") for (int n = 0; n < 2; ++n) _Pragma("unroll") for (int k = 0; k < 2; ++k) \
;         acc[ai][bj][m][n] = __builtin_amdgcn_mfma_f32_16x16x32_bf16(Bt[n][k], At[m][k], acc[ai][bj][m][n], 0, 0, 0); __builtin_amdgcn_s_setprio(0); } while (0)
; #define PG8_WAIT_V(n) asm volatile("s_waitcnt vmcnt(" #n ")" ::: "memory")
; #define PG8_WAIT_L(n) asm volatile("s_waitcnt lgkmcnt(" #n ")" ::: "memory")
; #define PG8_BAR __builtin_amdgcn_s_barrier()
; #define PG8_SCHED __builtin_amdgcn_sched_barrier(0)
; template <class Epi, bool ALIGN_EPI = true>
; __device__ __forceinline__ void gemm_phase(LAS unsigned char* lds, const Gemm g, const StaticOrder& S, const Epi& E) {
;     ...
;             PG8_WAIT_V(8); PG8_WAIT_L(0); PG8_BAR; PG8_MMA(1, 0, At, B0); PG8_MMA(1, 1, At, B1); PG8_BAR; PG8_SCHED;
;             PG8_LDB(B0, 1, 0); PG8_LDB(B1, 1, 1); PG8_SCHED; PG8_LDA(At, o1); PG8_STAGE(PG8_SA1(0), a2 + hstep, voffA); PG8_STAGE(o0, a3, voffA);
;             PG8_WAIT_V(10); PG8_WAIT_L(0); PG8_BAR; PG8_MMA(0, 0, At, B0); PG8_MMA(0, 1, At, B1); PG8_BAR; PG8_SCHED;
	s_setprio 1
	s_waitcnt lgkmcnt(0)
	v_mfma_f32_16x16x32_bf16 v[62:65], v[98:101], v[162:165], v[62:65]
	v_mfma_f32_16x16x32_bf16 v[62:65], v[110:113], v[166:169], v[62:65]
	v_mfma_f32_16x16x32_bf16 v[58:61], v[122:125], v[162:165], v[58:61]
	v_mfma_f32_16x16x32_bf16 v[58:61], v[134:137], v[166:169], v[58:61]
	v_mfma_f32_16x16x32_bf16 v[54:57], v[146:149], v[162:165], v[54:57]
	v_mfma_f32_16x16x32_bf16 v[54:57], v[150:153], v[166:169], v[54:57]
	v_mfma_f32_16x16x32_bf16 v[50:53], v[154:157], v[162:165], v[50:53]
	v_mfma_f32_16x16x32_bf16 v[50:53], v[158:161], v[166:169], v[50:53]
	v_mfma_f32_16x16x32_bf16 v[46:49], v[98:101], v[170:173], v[46:49]
	v_mfma_f32_16x16x32_bf16 v[46:49], v[110:113], v[190:193], v[46:49]
	v_mfma_f32_16x16x32_bf16 v[42:45], v[122:125], v[170:173], v[42:45]
	v_mfma_f32_16x16x32_bf16 v[42:45], v[134:137], v[190:193], v[42:45]
	v_mfma_f32_16x16x32_bf16 v[38:41], v[146:149], v[170:173], v[38:41]
	v_mfma_f32_16x16x32_bf16 v[38:41], v[150:153], v[190:193], v[38:41]
	v_mfma_f32_16x16x32_bf16 v[34:37], v[154:157], v[170:173], v[34:37]
	v_mfma_f32_16x16x32_bf16 v[34:37], v[158:161], v[190:193], v[34:37]
	s_setprio 0
	s_setprio 1
	v_mfma_f32_16x16x32_bf16 v[30:33], v[98:101], v[194:197], v[30:33]
	v_mfma_f32_16x16x32_bf16 v[30:33], v[110:113], v[198:201], v[30:33]
	v_mfma_f32_16x16x32_bf16 v[26:29], v[122:125], v[194:197], v[26:29]
	v_mfma_f32_16x16x32_bf16 v[26:29], v[134:137], v[198:201], v[26:29]
	v_mfma_f32_16x16x32_bf16 v[22:25], v[146:149], v[194:197], v[22:25]
	v_mfma_f32_16x16x32_bf16 v[22:25], v[150:153], v[198:201], v[22:25]
	v_mfma_f32_16x16x32_bf16 v[18:21], v[154:157], v[194:197], v[18:21]
	v_mfma_f32_16x16x32_bf16 v[18:21], v[158:161], v[198:201], v[18:21]
	v_mfma_f32_16x16x32_bf16 v[14:17], v[98:101], v[202:205], v[14:17]
	v_mfma_f32_16x16x32_bf16 v[14:17], v[110:113], v[210:213], v[14:17]
	v_mfma_f32_16x16x32_bf16 v[10:13], v[122:125], v[202:205], v[10:13]
	v_mfma_f32_16x16x32_bf16 v[10:13], v[134:137], v[210:213], v[10:13]
	v_mfma_f32_16x16x32_bf16 v[6:9], v[146:149], v[202:205], v[6:9]
	v_mfma_f32_16x16x32_bf16 v[6:9], v[150:153], v[210:213], v[6:9]
	v_mfma_f32_16x16x32_bf16 v[2:5], v[154:157], v[202:205], v[2:5]
	v_mfma_f32_16x16x32_bf16 v[2:5], v[158:161], v[210:213], v[2:5]
	s_setprio 0
	s_barrier
	s_add_i32 s63, 0, 0x10000
	s_add_i32 s64, 0, 0x14000
	v_add_u32_e32 v134, s63, v206
	v_add_u32_e32 v158, s64, v206
	ds_read_b128 v[98:101], v134
	ds_read_b128 v[110:113], v134 offset:1024
	ds_read_b128 v[122:125], v134 offset:2048
	ds_read_b128 v[134:137], v134 offset:3072
	ds_read_b128 v[146:149], v158
	ds_read_b128 v[150:153], v158 offset:1024
	ds_read_b128 v[154:157], v158 offset:2048
	ds_read_b128 v[158:161], v158 offset:3072
	s_add_u32 s44, s44, 0x80000
	s_addc_u32 s45, s45, 0
	s_mov_b32 m0, s39
	v_add_u32_e32 v210, s54, v207
	v_lshl_add_u64 v[222:223], s[44:45], 0, v[174:175]
	ds_read_b128 v[162:165], v210
	ds_read_b128 v[166:169], v210 offset:1024
	ds_read_b128 v[170:173], v210 offset:2048
	ds_read_b128 v[190:193], v210 offset:3072
	ds_read_b128 v[194:197], v210 offset:4096
	ds_read_b128 v[198:201], v210 offset:5120
	ds_read_b128 v[202:205], v210 offset:6144
	ds_read_b128 v[210:213], v210 offset:7168
	global_load_lds_dwordx4 v[222:223], off
	v_lshl_add_u64 v[222:223], s[44:45], 0, v[178:179]
	s_mov_b32 m0, s50
	s_add_i32 s44, s39, s52
	global_load_lds_dwordx4 v[222:223], off
	v_lshl_add_u64 v[214:215], v[214:215], 0, s[10:11]
	s_mov_b32 m0, s44
	s_nop 0
	global_load_lds_dwordx4 v[214:215], off
	v_lshl_add_u64 v[214:215], v[216:217], 0, s[10:11]
	s_add_i32 m0, s44, 0x2000
	s_nop 0
	global_load_lds_dwordx4 v[214:215], off
	s_waitcnt vmcnt(10)
	s_waitcnt lgkmcnt(0)
	s_barrier
; #define PG8_STAGE(bufoff, gbase, voff) do { _Pragma("unroll") for (int _i = 0; _i < 2; ++_i) \
;         __builtin_amdgcn_global_load_lds((const unsigned*)((const char*)(gbase) + (voff)[_i]), (LAS unsigned*)(lds + (bufoff) + ldsw + _i * 8192), 16, 0, 0); } while (0)
; #define PG8_LDA(dst, off) do { _Pragma("unroll") for (int m = 0; m < 4; ++m) _Pragma("unroll") for (int k = 0; k < 2; ++k) dst[m][k] = *(const LAS bf16x8*)(lds + (off) + aoff + m * 2048 + k * 1024); } while (0)
; #define PG8_MMA(ai, bj, At, Bt) do { __builtin_amdgcn_s_setprio(1); _Pragma("unroll") for (int m = 0; m < 4; ++m) _Pragma("unroll") for (int n = 0; n < 2; ++n) _Pragma("unroll") for (int k = 0; k < 2; ++k) \
;         acc[ai][bj][m][n] = __builtin_amdgcn_mfma_f32_16x16x32_bf16(Bt[n][k], At[m][k], acc[ai][bj][m][n], 0, 0, 0); __builtin_amdgcn_s_setprio(0); } while (0)
; #define PG8_WAIT_V(n) asm volatile("s_waitcnt vmcnt(" #n ")" ::: "memory")
; #define PG8_WAIT_L(n) asm volatile("s_waitcnt lgkmcnt(" #n ")" ::: "memory")
; #define PG8_BAR __builtin_amdgcn_s_barrier()
; #define PG8_SCHED __builtin_amdgcn_sched_barrier(0)
; template <class Epi, bool ALIGN_EPI = true>
; __device__ __forceinline__ void gemm_phase(LAS unsigned char* lds, const Gemm g, const StaticOrder& S, const Epi& E) {
;     ...
;             PG8_WAIT_V(10); PG8_WAIT_L(0); PG8_BAR; PG8_MMA(0, 0, At, B0); PG8_MMA(0, 1, At, B1); PG8_BAR; PG8_SCHED;
;             PG8_LDA(At, PG8_SA1(1)); PG8_STAGE(PG8_SB(1, 0), b3, voffB); PG8_STAGE(PG8_SB(1, 1), b3 + hstep, voffB);
;             PG8_WAIT_V(8); PG8_WAIT_L(0); PG8_BAR; PG8_MMA(1, 0, At, B0); PG8_MMA(1, 1, At, B1); PG8_BAR; PG8_SCHED;
;             { const int t_ = o0; o0 = o2; o2 = o1; o1 = t_; }
;         }
;         if constexpr (ALIGN_EPI) { if (wr == 0) PG8_BAR; }
	s_setprio 1
	s_waitcnt lgkmcnt(0)
	v_mfma_f32_16x16x32_bf16 v[86:89], v[98:101], v[162:165], v[86:89]
	v_mfma_f32_16x16x32_bf16 v[86:89], v[110:113], v[166:169], v[86:89]
	v_mfma_f32_16x16x32_bf16 v[74:77], v[122:125], v[162:165], v[74:77]
	v_mfma_f32_16x16x32_bf16 v[74:77], v[134:137], v[166:169], v[74:77]
	v_mfma_f32_16x16x32_bf16 v[142:145], v[146:149], v[162:165], v[142:145]
	v_mfma_f32_16x16x32_bf16 v[142:145], v[150:153], v[166:169], v[142:145]
	v_mfma_f32_16x16x32_bf16 v[138:141], v[154:157], v[162:165], v[138:141]
	v_mfma_f32_16x16x32_bf16 v[138:141], v[158:161], v[166:169], v[138:141]
	v_mfma_f32_16x16x32_bf16 v[130:133], v[98:101], v[170:173], v[130:133]
	v_mfma_f32_16x16x32_bf16 v[130:133], v[110:113], v[190:193], v[130:133]
	v_mfma_f32_16x16x32_bf16 v[126:129], v[122:125], v[170:173], v[126:129]
	v_mfma_f32_16x16x32_bf16 v[126:129], v[134:137], v[190:193], v[126:129]
	v_mfma_f32_16x16x32_bf16 v[118:121], v[146:149], v[170:173], v[118:121]
	v_mfma_f32_16x16x32_bf16 v[118:121], v[150:153], v[190:193], v[118:121]
	v_mfma_f32_16x16x32_bf16 v[114:117], v[154:157], v[170:173], v[114:117]
	v_mfma_f32_16x16x32_bf16 v[114:117], v[158:161], v[190:193], v[114:117]
	s_setprio 0
	s_setprio 1
	v_mfma_f32_16x16x32_bf16 v[106:109], v[98:101], v[194:197], v[106:109]
	v_mfma_f32_16x16x32_bf16 v[106:109], v[110:113], v[198:201], v[106:109]
	v_mfma_f32_16x16x32_bf16 v[102:105], v[122:125], v[194:197], v[102:105]
	v_mfma_f32_16x16x32_bf16 v[102:105], v[134:137], v[198:201], v[102:105]
	v_mfma_f32_16x16x32_bf16 v[94:97], v[146:149], v[194:197], v[94:97]
	v_mfma_f32_16x16x32_bf16 v[94:97], v[150:153], v[198:201], v[94:97]
	v_mfma_f32_16x16x32_bf16 v[90:93], v[154:157], v[194:197], v[90:93]
	v_mfma_f32_16x16x32_bf16 v[90:93], v[158:161], v[198:201], v[90:93]
	v_mfma_f32_16x16x32_bf16 v[82:85], v[98:101], v[202:205], v[82:85]
	v_mfma_f32_16x16x32_bf16 v[82:85], v[110:113], v[210:213], v[82:85]
	v_mfma_f32_16x16x32_bf16 v[78:81], v[122:125], v[202:205], v[78:81]
	v_mfma_f32_16x16x32_bf16 v[78:81], v[134:137], v[210:213], v[78:81]
	v_mfma_f32_16x16x32_bf16 v[70:73], v[146:149], v[202:205], v[70:73]
	v_mfma_f32_16x16x32_bf16 v[70:73], v[150:153], v[210:213], v[70:73]
	v_mfma_f32_16x16x32_bf16 v[66:69], v[154:157], v[202:205], v[66:69]
	v_mfma_f32_16x16x32_bf16 v[66:69], v[158:161], v[210:213], v[66:69]
	s_setprio 0
	s_barrier
	s_add_i32 s44, s63, s35
	v_lshl_add_u64 v[214:215], v[218:219], 0, s[10:11]
	s_mov_b32 m0, s44
	ds_read_b128 v[162:165], v207 offset:16384
	ds_read_b128 v[166:169], v207 offset:17408
	ds_read_b128 v[170:173], v207 offset:18432
	ds_read_b128 v[190:193], v207 offset:19456
	ds_read_b128 v[194:197], v207 offset:20480
	ds_read_b128 v[198:201], v207 offset:21504
	ds_read_b128 v[202:205], v207 offset:22528
	ds_read_b128 v[210:213], v207 offset:23552
	global_load_lds_dwordx4 v[214:215], off
	s_add_i32 m0, s44, 0x2000
	s_add_u32 s42, s42, 0x80080
	v_lshl_add_u64 v[214:215], v[220:221], 0, s[10:11]
	s_addc_u32 s43, s43, 0
	s_add_i32 s44, s64, s35
	global_load_lds_dwordx4 v[214:215], off
	v_lshl_add_u64 v[214:215], s[42:43], 0, v[176:177]
	s_mov_b32 m0, s44
	s_nop 0
	global_load_lds_dwordx4 v[214:215], off
	v_lshl_add_u64 v[214:215], s[42:43], 0, v[180:181]
	s_add_i32 m0, s44, 0x2000
	s_nop 0
	global_load_lds_dwordx4 v[214:215], off
	s_waitcnt vmcnt(8)
	s_waitcnt lgkmcnt(0)
	s_barrier
	s_setprio 1
	s_waitcnt lgkmcnt(0)
	v_mfma_f32_16x16x32_bf16 v[62:65], v[98:101], v[162:165], v[62:65]
	v_mfma_f32_16x16x32_bf16 v[62:65], v[110:113], v[166:169], v[62:65]
	v_mfma_f32_16x16x32_bf16 v[58:61], v[122:125], v[162:165], v[58:61]
	v_mfma_f32_16x16x32_bf16 v[58:61], v[134:137], v[166:169], v[58:61]
	v_mfma_f32_16x16x32_bf16 v[54:57], v[146:149], v[162:165], v[54:57]
	v_mfma_f32_16x16x32_bf16 v[54:57], v[150:153], v[166:169], v[54:57]
	v_mfma_f32_16x16x32_bf16 v[50:53], v[154:157], v[162:165], v[50:53]
	v_mfma_f32_16x16x32_bf16 v[50:53], v[158:161], v[166:169], v[50:53]
	v_mfma_f32_16x16x32_bf16 v[46:49], v[98:101], v[170:173], v[46:49]
	v_mfma_f32_16x16x32_bf16 v[46:49], v[110:113], v[190:193], v[46:49]
	v_mfma_f32_16x16x32_bf16 v[42:45], v[122:125], v[170:173], v[42:45]
	v_mfma_f32_16x16x32_bf16 v[42:45], v[134:137], v[190:193], v[42:45]
	v_mfma_f32_16x16x32_bf16 v[38:41], v[146:149], v[170:173], v[38:41]
	v_mfma_f32_16x16x32_bf16 v[38:41], v[150:153], v[190:193], v[38:41]
	v_mfma_f32_16x16x32_bf16 v[34:37], v[154:157], v[170:173], v[34:37]
	v_mfma_f32_16x16x32_bf16 v[34:37], v[158:161], v[190:193], v[34:37]
	s_setprio 0
	s_setprio 1
	v_mfma_f32_16x16x32_bf16 v[30:33], v[98:101], v[194:197], v[30:33]
	v_mfma_f32_16x16x32_bf16 v[30:33], v[110:113], v[198:201], v[30:33]
	v_mfma_f32_16x16x32_bf16 v[26:29], v[122:125], v[194:197], v[26:29]
	v_mfma_f32_16x16x32_bf16 v[26:29], v[134:137], v[198:201], v[26:29]
	v_mfma_f32_16x16x32_bf16 v[22:25], v[146:149], v[194:197], v[22:25]
	v_mfma_f32_16x16x32_bf16 v[22:25], v[150:153], v[198:201], v[22:25]
	v_mfma_f32_16x16x32_bf16 v[18:21], v[154:157], v[194:197], v[18:21]
	v_mfma_f32_16x16x32_bf16 v[18:21], v[158:161], v[198:201], v[18:21]
	v_mfma_f32_16x16x32_bf16 v[14:17], v[98:101], v[202:205], v[14:17]
	v_mfma_f32_16x16x32_bf16 v[14:17], v[110:113], v[210:213], v[14:17]
	v_mfma_f32_16x16x32_bf16 v[10:13], v[122:125], v[202:205], v[10:13]
	v_mfma_f32_16x16x32_bf16 v[10:13], v[134:137], v[210:213], v[10:13]
	v_mfma_f32_16x16x32_bf16 v[6:9], v[146:149], v[202:205], v[6:9]
	v_mfma_f32_16x16x32_bf16 v[6:9], v[150:153], v[210:213], v[6:9]
	v_mfma_f32_16x16x32_bf16 v[2:5], v[154:157], v[202:205], v[2:5]
	v_mfma_f32_16x16x32_bf16 v[2:5], v[158:161], v[210:213], v[2:5]
	s_setprio 0
	s_barrier
	s_add_i32 s62, s62, 2
	s_add_u32 s40, s40, 0x100
	s_addc_u32 s41, s41, 0
	s_add_u32 s60, s60, 0x100
	s_addc_u32 s61, s61, 0
	s_cmp_gt_u32 s62, 29
	s_mov_b32 s42, s56
	s_cbranch_scc0 .LBB0_610
	s_and_b64 vcc, exec, s[12:13]
	s_cbranch_vccz .LBB0_613
	s_barrier

; #define PG8_STAGE(bufoff, gbase, voff) do { _Pragma("unroll") for (int _i = 0; _i < 2; ++_i) \
;         __builtin_amdgcn_global_load_lds((const unsigned*)((const char*)(gbase) + (voff)[_i]), (LAS unsigned*)(lds + (bufoff) + ldsw + _i * 8192), 16, 0, 0); } while (0)
; #define PG8_LDA(dst, off) do { _Pragma("unroll") for (int m = 0; m < 4; ++m) _Pragma("unroll") for (int k = 0; k < 2; ++k) dst[m][k] = *(const LAS bf16x8*)(lds + (off) + aoff + m * 2048 + k * 1024); } while (0)
; #define PG8_LDB(dst, b, h) do { _Pragma("unroll") for (int n = 0; n < 2; ++n) _Pragma("unroll") for (int k = 0; k < 2; ++k) dst[n][k] = *(const LAS bf16x8*)(lds + PG8_SB(b, h) + boff + n * 2048 + k * 1024); } while (0)
; #define PG8_MMA(ai, bj, At, Bt) do { __builtin_amdgcn_s_setprio(1); _Pragma("unroll") for (int m = 0; m < 4; ++m) _Pragma("unroll") for (int n = 0; n < 2; ++n) _Pragma("unroll") for (int k = 0; k < 2; ++k) \
;         acc[ai][bj][m][n] = __builtin_amdgcn_mfma_f32_16x16x32_bf16(Bt[n][k], At[m][k], acc[ai][bj][m][n], 0, 0, 0); __builtin_amdgcn_s_setprio(0); } while (0)
; #define PG8_WAIT_V(n) asm volatile("s_waitcnt vmcnt(" #n ")" ::: "memory")
; #define PG8_WAIT_L(n) asm volatile("s_waitcnt lgkmcnt(" #n ")" ::: "memory")
; #define PG8_BAR __builtin_amdgcn_s_barrier()
; #define PG8_SCHED __builtin_amdgcn_sched_barrier(0)
; template <class Epi, bool ALIGN_EPI = true>
; __device__ __forceinline__ void gemm_phase(LAS unsigned char* lds, const Gemm g, const StaticOrder& S, const Epi& E) {
;     ...
;             const bool last = (t == nt - 2);
;             const char* a1 = cA + (size_t)(t + 1) * kstep;
;             const char* a2 = last ? nA : cA + (size_t)(t + 2) * kstep; const char* b2 = last ? nB : cB + (size_t)(t + 2) * kstep;
;             const char* a3 = a2 + kstep; const char* b3 = b2 + kstep;
;             PG8_LDB(B0, 0, 0); PG8_LDB(B1, 0, 1); PG8_SCHED; PG8_LDA(At, o0); PG8_STAGE(PG8_SA1(1), a1 + hstep, voffA); PG8_STAGE(o2, a2, voffA);
;             PG8_WAIT_V(10); PG8_WAIT_L(0); PG8_BAR; PG8_MMA(0, 0, At, B0); PG8_MMA(0, 1, At, B1); PG8_BAR; PG8_SCHED;
;             PG8_LDA(At, PG8_SA1(0)); PG8_STAGE(PG8_SB(0, 0), b2, voffB); PG8_STAGE(PG8_SB(0, 1), b2 + hstep, voffB);
;             PG8_WAIT_V(8); PG8_WAIT_L(0); PG8_BAR; PG8_MMA(1, 0, At, B0); PG8_MMA(1, 1, At, B1); PG8_BAR; PG8_SCHED;
.LBB0_689:
	ds_read_b128 v[130:133], v215 offset:32768
	ds_read_b128 v[134:137], v215 offset:33792
	ds_read_b128 v[138:141], v215 offset:34816
	ds_read_b128 v[142:145], v215 offset:35840
	ds_read_b128 v[146:149], v215 offset:49152
	ds_read_b128 v[150:153], v215 offset:50176
	ds_read_b128 v[154:157], v215 offset:51200
	ds_read_b128 v[158:161], v215 offset:52224
	s_mov_b32 s61, s57
	s_mov_b32 s57, s56
	s_mov_b32 s56, s12
	s_add_u32 s12, s10, 0xfff80080
	s_addc_u32 s13, s11, -1
	s_cmp_eq_u32 s66, 28
	s_cselect_b32 s46, s62, s12
	s_cselect_b32 s12, s63, s64
	s_cselect_b32 s47, s41, s13
	s_cselect_b32 s13, s39, s65
	v_add_u32_e32 v206, s56, v213
	v_lshl_add_u64 v[210:211], s[10:11], 0, v[186:187]
	s_add_i32 m0, s49, 0x4000
	ds_read_b128 v[162:165], v206
	ds_read_b128 v[166:169], v206 offset:1024
	ds_read_b128 v[170:173], v206 offset:2048
	ds_read_b128 v[174:177], v206 offset:3072
	ds_read_b128 v[194:197], v206 offset:4096
	ds_read_b128 v[198:201], v206 offset:5120
	ds_read_b128 v[202:205], v206 offset:6144
	ds_read_b128 v[206:209], v206 offset:7168
	global_load_lds_dwordx4 v[210:211], off
	v_lshl_add_u64 v[210:211], s[10:11], 0, v[188:189]
	s_add_i32 m0, s49, 0x6000
	s_add_i32 s67, s49, s61
	global_load_lds_dwordx4 v[210:211], off
	v_lshl_add_u64 v[210:211], s[46:47], 0, v[178:179]
	s_mov_b32 m0, s67
	v_lshl_add_u64 v[216:217], s[46:47], 0, v[182:183]
	global_load_lds_dwordx4 v[210:211], off
	s_add_i32 m0, s67, 0x2000
	s_nop 0
	global_load_lds_dwordx4 v[216:217], off
	s_waitcnt vmcnt(10)
	s_waitcnt lgkmcnt(0)
	s_barrier
	s_setprio 1
	s_waitcnt lgkmcnt(0)
	v_mfma_f32_16x16x32_bf16 v[126:129], v[130:133], v[162:165], v[126:129]
	v_mfma_f32_16x16x32_bf16 v[126:129], v[134:137], v[166:169], v[126:129]
	v_mfma_f32_16x16x32_bf16 v[122:125], v[138:141], v[162:165], v[122:125]
	v_mfma_f32_16x16x32_bf16 v[122:125], v[142:145], v[166:169], v[122:125]
	v_mfma_f32_16x16x32_bf16 v[118:121], v[146:149], v[162:165], v[118:121]
	v_mfma_f32_16x16x32_bf16 v[118:121], v[150:153], v[166:169], v[118:121]
	v_mfma_f32_16x16x32_bf16 v[114:117], v[154:157], v[162:165], v[114:117]
	v_mfma_f32_16x16x32_bf16 v[114:117], v[158:161], v[166:169], v[114:117]
	v_mfma_f32_16x16x32_bf16 v[110:113], v[130:133], v[170:173], v[110:113]
	v_mfma_f32_16x16x32_bf16 v[110:113], v[134:137], v[174:177], v[110:113]
	v_mfma_f32_16x16x32_bf16 v[106:109], v[138:141], v[170:173], v[106:109]
	v_mfma_f32_16x16x32_bf16 v[106:109], v[142:145], v[174:177], v[106:109]
	v_mfma_f32_16x16x32_bf16 v[102:105], v[146:149], v[170:173], v[102:105]
	v_mfma_f32_16x16x32_bf16 v[102:105], v[150:153], v[174:177], v[102:105]
	v_mfma_f32_16x16x32_bf16 v[98:101], v[154:157], v[170:173], v[98:101]
	v_mfma_f32_16x16x32_bf16 v[98:101], v[158:161], v[174:177], v[98:101]
	s_setprio 0
	s_setprio 1
	v_mfma_f32_16x16x32_bf16 v[94:97], v[130:133], v[194:197], v[94:97]
	v_mfma_f32_16x16x32_bf16 v[94:97], v[134:137], v[198:201], v[94:97]
	v_mfma_f32_16x16x32_bf16 v[90:93], v[138:141], v[194:197], v[90:93]
	v_mfma_f32_16x16x32_bf16 v[90:93], v[142:145], v[198:201], v[90:93]
	v_mfma_f32_16x16x32_bf16 v[86:89], v[146:149], v[194:197], v[86:89]
	v_mfma_f32_16x16x32_bf16 v[86:89], v[150:153], v[198:201], v[86:89]
	v_mfma_f32_16x16x32_bf16 v[82:85], v[154:157], v[194:197], v[82:85]
	v_mfma_f32_16x16x32_bf16 v[82:85], v[158:161], v[198:201], v[82:85]
	v_mfma_f32_16x16x32_bf16 v[78:81], v[130:133], v[202:205], v[78:81]
	v_mfma_f32_16x16x32_bf16 v[78:81], v[134:137], v[206:209], v[78:81]
	v_mfma_f32_16x16x32_bf16 v[74:77], v[138:141], v[202:205], v[74:77]
	v_mfma_f32_16x16x32_bf16 v[74:77], v[142:145], v[206:209], v[74:77]
	v_mfma_f32_16x16x32_bf16 v[70:73], v[146:149], v[202:205], v[70:73]
	v_mfma_f32_16x16x32_bf16 v[70:73], v[150:153], v[206:209], v[70:73]
	v_mfma_f32_16x16x32_bf16 v[66:69], v[154:157], v[202:205], v[66:69]
	v_mfma_f32_16x16x32_bf16 v[66:69], v[158:161], v[206:209], v[66:69]
	s_setprio 0
	s_barrier
	s_mov_b32 m0, s50
	v_lshl_add_u64 v[218:219], s[12:13], 0, v[180:181]
	s_add_u32 s68, s12, 0x80000
	ds_read_b128 v[162:165], v213
	ds_read_b128 v[166:169], v213 offset:1024
	ds_read_b128 v[170:173], v213 offset:2048
	ds_read_b128 v[174:177], v213 offset:3072
	ds_read_b128 v[194:197], v213 offset:4096
	ds_read_b128 v[198:201], v213 offset:5120
	ds_read_b128 v[202:205], v213 offset:6144
	ds_read_b128 v[206:209], v213 offset:7168
	global_load_lds_dwordx4 v[218:219], off
	v_lshl_add_u64 v[220:221], s[12:13], 0, v[184:185]
	s_mov_b32 m0, s51
	s_addc_u32 s69, s13, 0
	global_load_lds_dwordx4 v[220:221], off
	v_lshl_add_u64 v[222:223], s[68:69], 0, v[180:181]
	s_mov_b32 m0, s52
	s_nop 0
	global_load_lds_dwordx4 v[222:223], off
	v_lshl_add_u64 v[222:223], s[68:69], 0, v[184:185]
	s_mov_b32 m0, s53
	s_nop 0
	global_load_lds_dwordx4 v[222:223], off
	s_waitcnt vmcnt(8)
	s_waitcnt lgkmcnt(0)
	s_barrier
; #define PG8_STAGE(bufoff, gbase, voff) do { _Pragma("unroll") for (int _i = 0; _i < 2; ++_i) \
;         __builtin_amdgcn_global_load_lds((const unsigned*)((const char*)(gbase) + (voff)[_i]), (LAS unsigned*)(lds + (bufoff) + ldsw + _i * 8192), 16, 0, 0); } while (0)
; #define PG8_LDA(dst, off) do { _Pragma("unroll") for (int m = 0; m < 4; ++m) _Pragma("unroll") for (int k = 0; k < 2; ++k) dst[m][k] = *(const LAS bf16x8*)(lds + (off) + aoff + m * 2048 + k * 1024); } while (0)
; #define PG8_LDB(dst, b, h) do { _Pragma("unroll") for (int n = 0; n < 2; ++n) _Pragma("unroll") for (int k = 0; k < 2; ++k) dst[n][k] = *(const LAS bf16x8*)(lds + PG8_SB(b, h) + boff + n * 2048 + k * 1024); } while (0)
; #define PG8_MMA(ai, bj, At, Bt) do { __builtin_amdgcn_s_setprio(1); _Pragma("unroll") for (int m = 0; m < 4; ++m) _Pragma("unroll") for (int n = 0; n < 2; ++n) _Pragma("unroll") for (int k = 0; k < 2; ++k) \
;         acc[ai][bj][m][n] = __builtin_amdgcn_mfma_f32_16x16x32_bf16(Bt[n][k], At[m][k], acc[ai][bj][m][n], 0, 0, 0); __builtin_amdgcn_s_setprio(0); } while (0)
; #define PG8_WAIT_V(n) asm volatile("s_waitcnt vmcnt(" #n ")" ::: "memory")
; #define PG8_WAIT_L(n) asm volatile("s_waitcnt lgkmcnt(" #n ")" ::: "memory")
; #define PG8_BAR __builtin_amdgcn_s_barrier()
; #define PG8_SCHED __builtin_amdgcn_sched_barrier(0)
; template <class Epi, bool ALIGN_EPI = true>
; __device__ __forceinline__ void gemm_phase(LAS unsigned char* lds, const Gemm g, const StaticOrder& S, const Epi& E) {
;     ...
;             PG8_WAIT_V(8); PG8_WAIT_L(0); PG8_BAR; PG8_MMA(1, 0, At, B0); PG8_MMA(1, 1, At, B1); PG8_BAR; PG8_SCHED;
;             PG8_LDB(B0, 1, 0); PG8_LDB(B1, 1, 1); PG8_SCHED; PG8_LDA(At, o1); PG8_STAGE(PG8_SA1(0), a2 + hstep, voffA); PG8_STAGE(o0, a3, voffA);
;             PG8_WAIT_V(10); PG8_WAIT_L(0); PG8_BAR; PG8_MMA(0, 0, At, B0); PG8_MMA(0, 1, At, B1); PG8_BAR; PG8_SCHED;
	s_setprio 1
	s_waitcnt lgkmcnt(0)
	v_mfma_f32_16x16x32_bf16 v[62:65], v[130:133], v[162:165], v[62:65]
	v_mfma_f32_16x16x32_bf16 v[62:65], v[134:137], v[166:169], v[62:65]
	v_mfma_f32_16x16x32_bf16 v[58:61], v[138:141], v[162:165], v[58:61]
	v_mfma_f32_16x16x32_bf16 v[58:61], v[142:145], v[166:169], v[58:61]
	v_mfma_f32_16x16x32_bf16 v[54:57], v[146:149], v[162:165], v[54:57]
	v_mfma_f32_16x16x32_bf16 v[54:57], v[150:153], v[166:169], v[54:57]
	v_mfma_f32_16x16x32_bf16 v[50:53], v[154:157], v[162:165], v[50:53]
	v_mfma_f32_16x16x32_bf16 v[50:53], v[158:161], v[166:169], v[50:53]
	v_mfma_f32_16x16x32_bf16 v[46:49], v[130:133], v[170:173], v[46:49]
	v_mfma_f32_16x16x32_bf16 v[46:49], v[134:137], v[174:177], v[46:49]
	v_mfma_f32_16x16x32_bf16 v[42:45], v[138:141], v[170:173], v[42:45]
	v_mfma_f32_16x16x32_bf16 v[42:45], v[142:145], v[174:177], v[42:45]
	v_mfma_f32_16x16x32_bf16 v[38:41], v[146:149], v[170:173], v[38:41]
	v_mfma_f32_16x16x32_bf16 v[38:41], v[150:153], v[174:177], v[38:41]
	v_mfma_f32_16x16x32_bf16 v[34:37], v[154:157], v[170:173], v[34:37]
	v_mfma_f32_16x16x32_bf16 v[34:37], v[158:161], v[174:177], v[34:37]
	s_setprio 0
	s_setprio 1
	v_mfma_f32_16x16x32_bf16 v[30:33], v[130:133], v[194:197], v[30:33]
	v_mfma_f32_16x16x32_bf16 v[30:33], v[134:137], v[198:201], v[30:33]
	v_mfma_f32_16x16x32_bf16 v[26:29], v[138:141], v[194:197], v[26:29]
	v_mfma_f32_16x16x32_bf16 v[26:29], v[142:145], v[198:201], v[26:29]
	v_mfma_f32_16x16x32_bf16 v[22:25], v[146:149], v[194:197], v[22:25]
	v_mfma_f32_16x16x32_bf16 v[22:25], v[150:153], v[198:201], v[22:25]
	v_mfma_f32_16x16x32_bf16 v[18:21], v[154:157], v[194:197], v[18:21]
	v_mfma_f32_16x16x32_bf16 v[18:21], v[158:161], v[198:201], v[18:21]
	v_mfma_f32_16x16x32_bf16 v[14:17], v[130:133], v[202:205], v[14:17]
	v_mfma_f32_16x16x32_bf16 v[14:17], v[134:137], v[206:209], v[14:17]
	v_mfma_f32_16x16x32_bf16 v[10:13], v[138:141], v[202:205], v[10:13]
	v_mfma_f32_16x16x32_bf16 v[10:13], v[142:145], v[206:209], v[10:13]
	v_mfma_f32_16x16x32_bf16 v[6:9], v[146:149], v[202:205], v[6:9]
	v_mfma_f32_16x16x32_bf16 v[6:9], v[150:153], v[206:209], v[6:9]
	v_mfma_f32_16x16x32_bf16 v[2:5], v[154:157], v[202:205], v[2:5]
	v_mfma_f32_16x16x32_bf16 v[2:5], v[158:161], v[206:209], v[2:5]
	s_setprio 0
	s_barrier
	s_add_i32 s67, 0, 0x10000
	s_add_i32 s68, 0, 0x14000
	v_add_u32_e32 v142, s67, v212
	v_add_u32_e32 v158, s68, v212
	ds_read_b128 v[130:133], v142
	ds_read_b128 v[134:137], v142 offset:1024
	ds_read_b128 v[138:141], v142 offset:2048
	ds_read_b128 v[142:145], v142 offset:3072
	ds_read_b128 v[146:149], v158
	ds_read_b128 v[150:153], v158 offset:1024
	ds_read_b128 v[154:157], v158 offset:2048
	ds_read_b128 v[158:161], v158 offset:3072
	s_add_u32 s46, s46, 0x80000
	s_addc_u32 s47, s47, 0
	s_mov_b32 m0, s49
	v_add_u32_e32 v206, s57, v213
	v_lshl_add_u64 v[222:223], s[46:47], 0, v[178:179]
	ds_read_b128 v[162:165], v206
	ds_read_b128 v[166:169], v206 offset:1024
	ds_read_b128 v[170:173], v206 offset:2048
	ds_read_b128 v[174:177], v206 offset:3072
	ds_read_b128 v[194:197], v206 offset:4096
	ds_read_b128 v[198:201], v206 offset:5120
	ds_read_b128 v[202:205], v206 offset:6144
	ds_read_b128 v[206:209], v206 offset:7168
	global_load_lds_dwordx4 v[222:223], off
	v_lshl_add_u64 v[222:223], s[46:47], 0, v[182:183]
	s_mov_b32 m0, s54
	s_add_i32 s46, s49, s56
	global_load_lds_dwordx4 v[222:223], off
	v_lshl_add_u64 v[210:211], v[210:211], 0, s[24:25]
	s_mov_b32 m0, s46
	s_nop 0
	global_load_lds_dwordx4 v[210:211], off
	v_lshl_add_u64 v[210:211], v[216:217], 0, s[24:25]
	s_add_i32 m0, s46, 0x2000
	s_nop 0
	global_load_lds_dwordx4 v[210:211], off
	s_waitcnt vmcnt(10)
	s_waitcnt lgkmcnt(0)
	s_barrier
; #define PG8_STAGE(bufoff, gbase, voff) do { _Pragma("unroll") for (int _i = 0; _i < 2; ++_i) \
;         __builtin_amdgcn_global_load_lds((const unsigned*)((const char*)(gbase) + (voff)[_i]), (LAS unsigned*)(lds + (bufoff) + ldsw + _i * 8192), 16, 0, 0); } while (0)
; #define PG8_LDA(dst, off) do { _Pragma("unroll") for (int m = 0; m < 4; ++m) _Pragma("unroll") for (int k = 0; k < 2; ++k) dst[m][k] = *(const LAS bf16x8*)(lds + (off) + aoff + m * 2048 + k * 1024); } while (0)
; #define PG8_MMA(ai, bj, At, Bt) do { __builtin_amdgcn_s_setprio(1); _Pragma("unroll") for (int m = 0; m < 4; ++m) _Pragma("unroll") for (int n = 0; n < 2; ++n) _Pragma("unroll") for (int k = 0; k < 2; ++k) \
;         acc[ai][bj][m][n] = __builtin_amdgcn_mfma_f32_16x16x32_bf16(Bt[n][k], At[m][k], acc[ai][bj][m][n], 0, 0, 0); __builtin_amdgcn_s_setprio(0); } while (0)
; #define PG8_WAIT_V(n) asm volatile("s_waitcnt vmcnt(" #n ")" ::: "memory")
; #define PG8_WAIT_L(n) asm volatile("s_waitcnt lgkmcnt(" #n ")" ::: "memory")
; #define PG8_BAR __builtin_amdgcn_s_barrier()
; #define PG8_SCHED __builtin_amdgcn_sched_barrier(0)
; template <class Epi, bool ALIGN_EPI = true>
; __device__ __forceinline__ void gemm_phase(LAS unsigned char* lds, const Gemm g, const StaticOrder& S, const Epi& E) {
;     ...
;             PG8_WAIT_V(10); PG8_WAIT_L(0); PG8_BAR; PG8_MMA(0, 0, At, B0); PG8_MMA(0, 1, At, B1); PG8_BAR; PG8_SCHED;
;             PG8_LDA(At, PG8_SA1(1)); PG8_STAGE(PG8_SB(1, 0), b3, voffB); PG8_STAGE(PG8_SB(1, 1), b3 + hstep, voffB);
;             PG8_WAIT_V(8); PG8_WAIT_L(0); PG8_BAR; PG8_MMA(1, 0, At, B0); PG8_MMA(1, 1, At, B1); PG8_BAR; PG8_SCHED;
;             { const int t_ = o0; o0 = o2; o2 = o1; o1 = t_; }
;         }
;         if constexpr (ALIGN_EPI) { if (wr == 0) PG8_BAR; }
	s_setprio 1
	s_waitcnt lgkmcnt(0)
	v_mfma_f32_16x16x32_bf16 v[126:129], v[130:133], v[162:165], v[126:129]
	v_mfma_f32_16x16x32_bf16 v[126:129], v[134:137], v[166:169], v[126:129]
	v_mfma_f32_16x16x32_bf16 v[122:125], v[138:141], v[162:165], v[122:125]
	v_mfma_f32_16x16x32_bf16 v[122:125], v[142:145], v[166:169], v[122:125]
	v_mfma_f32_16x16x32_bf16 v[118:121], v[146:149], v[162:165], v[118:121]
	v_mfma_f32_16x16x32_bf16 v[118:121], v[150:153], v[166:169], v[118:121]
	v_mfma_f32_16x16x32_bf16 v[114:117], v[154:157], v[162:165], v[114:117]
	v_mfma_f32_16x16x32_bf16 v[114:117], v[158:161], v[166:169], v[114:117]
	v_mfma_f32_16x16x32_bf16 v[110:113], v[130:133], v[170:173], v[110:113]
	v_mfma_f32_16x16x32_bf16 v[110:113], v[134:137], v[174:177], v[110:113]
	v_mfma_f32_16x16x32_bf16 v[106:109], v[138:141], v[170:173], v[106:109]
	v_mfma_f32_16x16x32_bf16 v[106:109], v[142:145], v[174:177], v[106:109]
	v_mfma_f32_16x16x32_bf16 v[102:105], v[146:149], v[170:173], v[102:105]
	v_mfma_f32_16x16x32_bf16 v[102:105], v[150:153], v[174:177], v[102:105]
	v_mfma_f32_16x16x32_bf16 v[98:101], v[154:157], v[170:173], v[98:101]
	v_mfma_f32_16x16x32_bf16 v[98:101], v[158:161], v[174:177], v[98:101]
	s_setprio 0
	s_setprio 1
	v_mfma_f32_16x16x32_bf16 v[94:97], v[130:133], v[194:197], v[94:97]
	v_mfma_f32_16x16x32_bf16 v[94:97], v[134:137], v[198:201], v[94:97]
	v_mfma_f32_16x16x32_bf16 v[90:93], v[138:141], v[194:197], v[90:93]
	v_mfma_f32_16x16x32_bf16 v[90:93], v[142:145], v[198:201], v[90:93]
	v_mfma_f32_16x16x32_bf16 v[86:89], v[146:149], v[194:197], v[86:89]
	v_mfma_f32_16x16x32_bf16 v[86:89], v[150:153], v[198:201], v[86:89]
	v_mfma_f32_16x16x32_bf16 v[82:85], v[154:157], v[194:197], v[82:85]
	v_mfma_f32_16x16x32_bf16 v[82:85], v[158:161], v[198:201], v[82:85]
	v_mfma_f32_16x16x32_bf16 v[78:81], v[130:133], v[202:205], v[78:81]
	v_mfma_f32_16x16x32_bf16 v[78:81], v[134:137], v[206:209], v[78:81]
	v_mfma_f32_16x16x32_bf16 v[74:77], v[138:141], v[202:205], v[74:77]
	v_mfma_f32_16x16x32_bf16 v[74:77], v[142:145], v[206:209], v[74:77]
	v_mfma_f32_16x16x32_bf16 v[70:73], v[146:149], v[202:205], v[70:73]
	v_mfma_f32_16x16x32_bf16 v[70:73], v[150:153], v[206:209], v[70:73]
	v_mfma_f32_16x16x32_bf16 v[66:69], v[154:157], v[202:205], v[66:69]
	v_mfma_f32_16x16x32_bf16 v[66:69], v[158:161], v[206:209], v[66:69]
	s_setprio 0
	s_barrier
	s_add_i32 s46, s67, s48
	v_lshl_add_u64 v[210:211], v[218:219], 0, s[24:25]
	s_mov_b32 m0, s46
	ds_read_b128 v[162:165], v213 offset:16384
	ds_read_b128 v[166:169], v213 offset:17408
	ds_read_b128 v[170:173], v213 offset:18432
	ds_read_b128 v[174:177], v213 offset:19456
	ds_read_b128 v[194:197], v213 offset:20480
	ds_read_b128 v[198:201], v213 offset:21504
	ds_read_b128 v[202:205], v213 offset:22528
	ds_read_b128 v[206:209], v213 offset:23552
	global_load_lds_dwordx4 v[210:211], off
	s_add_i32 m0, s46, 0x2000
	s_add_u32 s12, s12, 0x80080
	v_lshl_add_u64 v[210:211], v[220:221], 0, s[24:25]
	s_addc_u32 s13, s13, 0
	s_add_i32 s46, s68, s48
	global_load_lds_dwordx4 v[210:211], off
	v_lshl_add_u64 v[210:211], s[12:13], 0, v[180:181]
	s_mov_b32 m0, s46
	s_nop 0
	global_load_lds_dwordx4 v[210:211], off
	v_lshl_add_u64 v[210:211], s[12:13], 0, v[184:185]
	s_add_i32 m0, s46, 0x2000
	s_nop 0
	global_load_lds_dwordx4 v[210:211], off
	s_waitcnt vmcnt(8)
	s_waitcnt lgkmcnt(0)
	s_barrier
	s_setprio 1
	s_waitcnt lgkmcnt(0)
	v_mfma_f32_16x16x32_bf16 v[62:65], v[130:133], v[162:165], v[62:65]
	v_mfma_f32_16x16x32_bf16 v[62:65], v[134:137], v[166:169], v[62:65]
	v_mfma_f32_16x16x32_bf16 v[58:61], v[138:141], v[162:165], v[58:61]
	v_mfma_f32_16x16x32_bf16 v[58:61], v[142:145], v[166:169], v[58:61]
	v_mfma_f32_16x16x32_bf16 v[54:57], v[146:149], v[162:165], v[54:57]
	v_mfma_f32_16x16x32_bf16 v[54:57], v[150:153], v[166:169], v[54:57]
	v_mfma_f32_16x16x32_bf16 v[50:53], v[154:157], v[162:165], v[50:53]
	v_mfma_f32_16x16x32_bf16 v[50:53], v[158:161], v[166:169], v[50:53]
	v_mfma_f32_16x16x32_bf16 v[46:49], v[130:133], v[170:173], v[46:49]
	v_mfma_f32_16x16x32_bf16 v[46:49], v[134:137], v[174:177], v[46:49]
	v_mfma_f32_16x16x32_bf16 v[42:45], v[138:141], v[170:173], v[42:45]
	v_mfma_f32_16x16x32_bf16 v[42:45], v[142:145], v[174:177], v[42:45]
	v_mfma_f32_16x16x32_bf16 v[38:41], v[146:149], v[170:173], v[38:41]
	v_mfma_f32_16x16x32_bf16 v[38:41], v[150:153], v[174:177], v[38:41]
	v_mfma_f32_16x16x32_bf16 v[34:37], v[154:157], v[170:173], v[34:37]
	v_mfma_f32_16x16x32_bf16 v[34:37], v[158:161], v[174:177], v[34:37]
	s_setprio 0
	s_setprio 1
	v_mfma_f32_16x16x32_bf16 v[30:33], v[130:133], v[194:197], v[30:33]
	v_mfma_f32_16x16x32_bf16 v[30:33], v[134:137], v[198:201], v[30:33]
	v_mfma_f32_16x16x32_bf16 v[26:29], v[138:141], v[194:197], v[26:29]
	v_mfma_f32_16x16x32_bf16 v[26:29], v[142:145], v[198:201], v[26:29]
	v_mfma_f32_16x16x32_bf16 v[22:25], v[146:149], v[194:197], v[22:25]
	v_mfma_f32_16x16x32_bf16 v[22:25], v[150:153], v[198:201], v[22:25]
	v_mfma_f32_16x16x32_bf16 v[18:21], v[154:157], v[194:197], v[18:21]
	v_mfma_f32_16x16x32_bf16 v[18:21], v[158:161], v[198:201], v[18:21]
	v_mfma_f32_16x16x32_bf16 v[14:17], v[130:133], v[202:205], v[14:17]
	v_mfma_f32_16x16x32_bf16 v[14:17], v[134:137], v[206:209], v[14:17]
	v_mfma_f32_16x16x32_bf16 v[10:13], v[138:141], v[202:205], v[10:13]
	v_mfma_f32_16x16x32_bf16 v[10:13], v[142:145], v[206:209], v[10:13]
	v_mfma_f32_16x16x32_bf16 v[6:9], v[146:149], v[202:205], v[6:9]
	v_mfma_f32_16x16x32_bf16 v[6:9], v[150:153], v[206:209], v[6:9]
	v_mfma_f32_16x16x32_bf16 v[2:5], v[154:157], v[202:205], v[2:5]
	v_mfma_f32_16x16x32_bf16 v[2:5], v[158:161], v[206:209], v[2:5]
	s_setprio 0
	s_barrier
	s_add_i32 s66, s66, 2
	s_add_u32 s10, s10, 0x100
	s_addc_u32 s11, s11, 0
	s_add_u32 s64, s64, 0x100
	s_addc_u32 s65, s65, 0
	s_cmp_gt_u32 s66, 29
	s_mov_b32 s12, s61
	s_cbranch_scc0 .LBB0_689
	s_and_b64 vcc, exec, s[26:27]
	s_cbranch_vccz .LBB0_692
	s_barrier

; #define PG8_STAGE(bufoff, gbase, voff) do { _Pragma("unroll") for (int _i = 0; _i < 2; ++_i) \
;         __builtin_amdgcn_global_load_lds((const unsigned*)((const char*)(gbase) + (voff)[_i]), (LAS unsigned*)(lds + (bufoff) + ldsw + _i * 8192), 16, 0, 0); } while (0)
; #define PG8_LDA(dst, off) do { _Pragma("unroll") for (int m = 0; m < 4; ++m) _Pragma("unroll") for (int k = 0; k < 2; ++k) dst[m][k] = *(const LAS bf16x8*)(lds + (off) + aoff + m * 2048 + k * 1024); } while (0)
; #define PG8_LDB(dst, b, h) do { _Pragma("unroll") for (int n = 0; n < 2; ++n) _Pragma("unroll") for (int k = 0; k < 2; ++k) dst[n][k] = *(const LAS bf16x8*)(lds + PG8_SB(b, h) + boff + n * 2048 + k * 1024); } while (0)
; #define PG8_MMA(ai, bj, At, Bt) do { __builtin_amdgcn_s_setprio(1); _Pragma("unroll") for (int m = 0; m < 4; ++m) _Pragma("unroll") for (int n = 0; n < 2; ++n) _Pragma("unroll") for (int k = 0; k < 2; ++k) \
;         acc[ai][bj][m][n] = __builtin_amdgcn_mfma_f32_16x16x32_bf16(Bt[n][k], At[m][k], acc[ai][bj][m][n], 0, 0, 0); __builtin_amdgcn_s_setprio(0); } while (0)
; #define PG8_WAIT_V(n) asm volatile("s_waitcnt vmcnt(" #n ")" ::: "memory")
; #define PG8_WAIT_L(n) asm volatile("s_waitcnt lgkmcnt(" #n ")" ::: "memory")
; #define PG8_BAR __builtin_amdgcn_s_barrier()
; #define PG8_SCHED __builtin_amdgcn_sched_barrier(0)
; template <class Epi, bool ALIGN_EPI = true>
; __device__ __forceinline__ void gemm_phase(LAS unsigned char* lds, const Gemm g, const StaticOrder& S, const Epi& E) {
;     ...
;             const bool last = (t == nt - 2);
;             const char* a1 = cA + (size_t)(t + 1) * kstep;
;             const char* a2 = last ? nA : cA + (size_t)(t + 2) * kstep; const char* b2 = last ? nB : cB + (size_t)(t + 2) * kstep;
;             const char* a3 = a2 + kstep; const char* b3 = b2 + kstep;
;             PG8_LDB(B0, 0, 0); PG8_LDB(B1, 0, 1); PG8_SCHED; PG8_LDA(At, o0); PG8_STAGE(PG8_SA1(1), a1 + hstep, voffA); PG8_STAGE(o2, a2, voffA);
;             PG8_WAIT_V(10); PG8_WAIT_L(0); PG8_BAR; PG8_MMA(0, 0, At, B0); PG8_MMA(0, 1, At, B1); PG8_BAR; PG8_SCHED;
;             PG8_LDA(At, PG8_SA1(0)); PG8_STAGE(PG8_SB(0, 0), b2, voffB); PG8_STAGE(PG8_SB(0, 1), b2 + hstep, voffB);
;             PG8_WAIT_V(8); PG8_WAIT_L(0); PG8_BAR; PG8_MMA(1, 0, At, B0); PG8_MMA(1, 1, At, B1); PG8_BAR; PG8_SCHED;
.LBB0_772:
	ds_read_b128 v[130:133], v179 offset:32768
	ds_read_b128 v[134:137], v179 offset:33792
	ds_read_b128 v[138:141], v179 offset:34816
	ds_read_b128 v[142:145], v179 offset:35840
	ds_read_b128 v[146:149], v179 offset:49152
	ds_read_b128 v[150:153], v179 offset:50176
	ds_read_b128 v[170:173], v179 offset:51200
	ds_read_b128 v[180:183], v179 offset:52224
	s_mov_b32 s51, s50
	s_mov_b32 s50, s48
	s_mov_b32 s48, s28
	s_add_u32 s28, s26, 0xfff00080
	s_addc_u32 s29, s27, -1
	s_cmp_eq_u32 s57, 60
	s_cselect_b32 s38, s53, s28
	s_cselect_b32 s28, s54, s55
	s_cselect_b32 s39, s13, s29
	s_cselect_b32 s29, s11, s56
	v_add_u32_e32 v174, s48, v177
	ds_read_b128 v[184:187], v174
	ds_read_b128 v[188:191], v174 offset:1024
	ds_read_b128 v[192:195], v174 offset:2048
	ds_read_b128 v[196:199], v174 offset:3072
	ds_read_b128 v[200:203], v174 offset:4096
	ds_read_b128 v[204:207], v174 offset:5120
	ds_read_b128 v[208:211], v174 offset:6144
	ds_read_b128 v[212:215], v174 offset:7168
	v_lshl_add_u64 v[174:175], s[26:27], 0, v[162:163]
	s_add_i32 m0, s25, 0x4000
	s_add_i32 s58, s25, s51
	global_load_lds_dwordx4 v[174:175], off
	v_lshl_add_u64 v[174:175], s[26:27], 0, v[164:165]
	s_add_i32 m0, s25, 0x6000
	v_lshl_add_u64 v[216:217], s[38:39], 0, v[158:159]
	global_load_lds_dwordx4 v[174:175], off
	v_lshl_add_u64 v[174:175], s[38:39], 0, v[154:155]
	s_mov_b32 m0, s58
	s_nop 0
	global_load_lds_dwordx4 v[174:175], off
	s_add_i32 m0, s58, 0x2000
	s_nop 0
	global_load_lds_dwordx4 v[216:217], off
	s_waitcnt vmcnt(10)
	s_waitcnt lgkmcnt(0)
	s_barrier
	s_setprio 1
	s_waitcnt lgkmcnt(0)
	v_mfma_f32_16x16x32_bf16 v[126:129], v[130:133], v[184:187], v[126:129]
	v_mfma_f32_16x16x32_bf16 v[126:129], v[134:137], v[188:191], v[126:129]
	v_mfma_f32_16x16x32_bf16 v[122:125], v[138:141], v[184:187], v[122:125]
	v_mfma_f32_16x16x32_bf16 v[122:125], v[142:145], v[188:191], v[122:125]
	v_mfma_f32_16x16x32_bf16 v[110:113], v[146:149], v[184:187], v[110:113]
	v_mfma_f32_16x16x32_bf16 v[110:113], v[150:153], v[188:191], v[110:113]
	v_mfma_f32_16x16x32_bf16 v[106:109], v[170:173], v[184:187], v[106:109]
	v_mfma_f32_16x16x32_bf16 v[106:109], v[180:183], v[188:191], v[106:109]
	v_mfma_f32_16x16x32_bf16 v[118:121], v[130:133], v[192:195], v[118:121]
	v_mfma_f32_16x16x32_bf16 v[118:121], v[134:137], v[196:199], v[118:121]
	v_mfma_f32_16x16x32_bf16 v[114:117], v[138:141], v[192:195], v[114:117]
	v_mfma_f32_16x16x32_bf16 v[114:117], v[142:145], v[196:199], v[114:117]
	v_mfma_f32_16x16x32_bf16 v[102:105], v[146:149], v[192:195], v[102:105]
	v_mfma_f32_16x16x32_bf16 v[102:105], v[150:153], v[196:199], v[102:105]
	v_mfma_f32_16x16x32_bf16 v[98:101], v[170:173], v[192:195], v[98:101]
	v_mfma_f32_16x16x32_bf16 v[98:101], v[180:183], v[196:199], v[98:101]
	s_setprio 0
	s_setprio 1
	v_mfma_f32_16x16x32_bf16 v[94:97], v[130:133], v[200:203], v[94:97]
	v_mfma_f32_16x16x32_bf16 v[94:97], v[134:137], v[204:207], v[94:97]
	v_mfma_f32_16x16x32_bf16 v[90:93], v[138:141], v[200:203], v[90:93]
	v_mfma_f32_16x16x32_bf16 v[90:93], v[142:145], v[204:207], v[90:93]
	v_mfma_f32_16x16x32_bf16 v[86:89], v[146:149], v[200:203], v[86:89]
	v_mfma_f32_16x16x32_bf16 v[86:89], v[150:153], v[204:207], v[86:89]
	v_mfma_f32_16x16x32_bf16 v[78:81], v[170:173], v[200:203], v[78:81]
	v_mfma_f32_16x16x32_bf16 v[78:81], v[180:183], v[204:207], v[78:81]
	v_mfma_f32_16x16x32_bf16 v[82:85], v[130:133], v[208:211], v[82:85]
	v_mfma_f32_16x16x32_bf16 v[82:85], v[134:137], v[212:215], v[82:85]
	v_mfma_f32_16x16x32_bf16 v[74:77], v[138:141], v[208:211], v[74:77]
	v_mfma_f32_16x16x32_bf16 v[74:77], v[142:145], v[212:215], v[74:77]
	v_mfma_f32_16x16x32_bf16 v[70:73], v[146:149], v[208:211], v[70:73]
	v_mfma_f32_16x16x32_bf16 v[70:73], v[150:153], v[212:215], v[70:73]
	v_mfma_f32_16x16x32_bf16 v[66:69], v[170:173], v[208:211], v[66:69]
	v_mfma_f32_16x16x32_bf16 v[66:69], v[180:183], v[212:215], v[66:69]
	s_setprio 0
	s_barrier
	s_mov_b32 m0, s40
	v_lshl_add_u64 v[218:219], s[28:29], 0, v[156:157]
	s_add_u32 s58, s28, 0x100000
	ds_read_b128 v[184:187], v177
	ds_read_b128 v[188:191], v177 offset:1024
	ds_read_b128 v[192:195], v177 offset:2048
	ds_read_b128 v[196:199], v177 offset:3072
	ds_read_b128 v[200:203], v177 offset:4096
	ds_read_b128 v[204:207], v177 offset:5120
	ds_read_b128 v[208:211], v177 offset:6144
	ds_read_b128 v[212:215], v177 offset:7168
	global_load_lds_dwordx4 v[218:219], off
	v_lshl_add_u64 v[220:221], s[28:29], 0, v[160:161]
	s_mov_b32 m0, s41
	s_addc_u32 s59, s29, 0
	global_load_lds_dwordx4 v[220:221], off
	v_lshl_add_u64 v[222:223], s[58:59], 0, v[156:157]
	s_mov_b32 m0, s42
	s_nop 0
	global_load_lds_dwordx4 v[222:223], off
	v_lshl_add_u64 v[222:223], s[58:59], 0, v[160:161]
	s_mov_b32 m0, s43
	s_nop 0
	global_load_lds_dwordx4 v[222:223], off
	s_waitcnt vmcnt(8)
	s_waitcnt lgkmcnt(0)
	s_barrier
; #define PG8_STAGE(bufoff, gbase, voff) do { _Pragma("unroll") for (int _i = 0; _i < 2; ++_i) \
;         __builtin_amdgcn_global_load_lds((const unsigned*)((const char*)(gbase) + (voff)[_i]), (LAS unsigned*)(lds + (bufoff) + ldsw + _i * 8192), 16, 0, 0); } while (0)
; #define PG8_LDA(dst, off) do { _Pragma("unroll") for (int m = 0; m < 4; ++m) _Pragma("unroll") for (int k = 0; k < 2; ++k) dst[m][k] = *(const LAS bf16x8*)(lds + (off) + aoff + m * 2048 + k * 1024); } while (0)
; #define PG8_LDB(dst, b, h) do { _Pragma("unroll") for (int n = 0; n < 2; ++n) _Pragma("unroll") for (int k = 0; k < 2; ++k) dst[n][k] = *(const LAS bf16x8*)(lds + PG8_SB(b, h) + boff + n * 2048 + k * 1024); } while (0)
; #define PG8_MMA(ai, bj, At, Bt) do { __builtin_amdgcn_s_setprio(1); _Pragma("unroll") for (int m = 0; m < 4; ++m) _Pragma("unroll") for (int n = 0; n < 2; ++n) _Pragma("unroll") for (int k = 0; k < 2; ++k) \
;         acc[ai][bj][m][n] = __builtin_amdgcn_mfma_f32_16x16x32_bf16(Bt[n][k], At[m][k], acc[ai][bj][m][n], 0, 0, 0); __builtin_amdgcn_s_setprio(0); } while (0)
; #define PG8_WAIT_V(n) asm volatile("s_waitcnt vmcnt(" #n ")" ::: "memory")
; #define PG8_WAIT_L(n) asm volatile("s_waitcnt lgkmcnt(" #n ")" ::: "memory")
; #define PG8_BAR __builtin_amdgcn_s_barrier()
; #define PG8_SCHED __builtin_amdgcn_sched_barrier(0)
; template <class Epi, bool ALIGN_EPI = true>
; __device__ __forceinline__ void gemm_phase(LAS unsigned char* lds, const Gemm g, const StaticOrder& S, const Epi& E) {
;     ...
;             PG8_WAIT_V(8); PG8_WAIT_L(0); PG8_BAR; PG8_MMA(1, 0, At, B0); PG8_MMA(1, 1, At, B1); PG8_BAR; PG8_SCHED;
;             PG8_LDB(B0, 1, 0); PG8_LDB(B1, 1, 1); PG8_SCHED; PG8_LDA(At, o1); PG8_STAGE(PG8_SA1(0), a2 + hstep, voffA); PG8_STAGE(o0, a3, voffA);
;             PG8_WAIT_V(10); PG8_WAIT_L(0); PG8_BAR; PG8_MMA(0, 0, At, B0); PG8_MMA(0, 1, At, B1); PG8_BAR; PG8_SCHED;
	s_setprio 1
	s_waitcnt lgkmcnt(0)
	v_mfma_f32_16x16x32_bf16 v[62:65], v[130:133], v[184:187], v[62:65]
	v_mfma_f32_16x16x32_bf16 v[62:65], v[134:137], v[188:191], v[62:65]
	v_mfma_f32_16x16x32_bf16 v[58:61], v[138:141], v[184:187], v[58:61]
	v_mfma_f32_16x16x32_bf16 v[58:61], v[142:145], v[188:191], v[58:61]
	v_mfma_f32_16x16x32_bf16 v[54:57], v[146:149], v[184:187], v[54:57]
	v_mfma_f32_16x16x32_bf16 v[54:57], v[150:153], v[188:191], v[54:57]
	v_mfma_f32_16x16x32_bf16 v[46:49], v[170:173], v[184:187], v[46:49]
	v_mfma_f32_16x16x32_bf16 v[46:49], v[180:183], v[188:191], v[46:49]
	v_mfma_f32_16x16x32_bf16 v[50:53], v[130:133], v[192:195], v[50:53]
	v_mfma_f32_16x16x32_bf16 v[50:53], v[134:137], v[196:199], v[50:53]
	v_mfma_f32_16x16x32_bf16 v[42:45], v[138:141], v[192:195], v[42:45]
	v_mfma_f32_16x16x32_bf16 v[42:45], v[142:145], v[196:199], v[42:45]
	v_mfma_f32_16x16x32_bf16 v[38:41], v[146:149], v[192:195], v[38:41]
	v_mfma_f32_16x16x32_bf16 v[38:41], v[150:153], v[196:199], v[38:41]
	v_mfma_f32_16x16x32_bf16 v[30:33], v[170:173], v[192:195], v[30:33]
	v_mfma_f32_16x16x32_bf16 v[30:33], v[180:183], v[196:199], v[30:33]
	s_setprio 0
	s_setprio 1
	v_mfma_f32_16x16x32_bf16 v[34:37], v[130:133], v[200:203], v[34:37]
	v_mfma_f32_16x16x32_bf16 v[34:37], v[134:137], v[204:207], v[34:37]
	v_mfma_f32_16x16x32_bf16 v[26:29], v[138:141], v[200:203], v[26:29]
	v_mfma_f32_16x16x32_bf16 v[26:29], v[142:145], v[204:207], v[26:29]
	v_mfma_f32_16x16x32_bf16 v[22:25], v[146:149], v[200:203], v[22:25]
	v_mfma_f32_16x16x32_bf16 v[22:25], v[150:153], v[204:207], v[22:25]
	v_mfma_f32_16x16x32_bf16 v[14:17], v[170:173], v[200:203], v[14:17]
	v_mfma_f32_16x16x32_bf16 v[14:17], v[180:183], v[204:207], v[14:17]
	v_mfma_f32_16x16x32_bf16 v[18:21], v[130:133], v[208:211], v[18:21]
	v_mfma_f32_16x16x32_bf16 v[18:21], v[134:137], v[212:215], v[18:21]
	v_mfma_f32_16x16x32_bf16 v[10:13], v[138:141], v[208:211], v[10:13]
	v_mfma_f32_16x16x32_bf16 v[10:13], v[142:145], v[212:215], v[10:13]
	v_mfma_f32_16x16x32_bf16 v[6:9], v[146:149], v[208:211], v[6:9]
	v_mfma_f32_16x16x32_bf16 v[6:9], v[150:153], v[212:215], v[6:9]
	v_mfma_f32_16x16x32_bf16 v[2:5], v[170:173], v[208:211], v[2:5]
	v_mfma_f32_16x16x32_bf16 v[2:5], v[180:183], v[212:215], v[2:5]
	s_setprio 0
	s_barrier
	s_add_i32 s58, 0, 0x10000
	s_add_i32 s59, 0, 0x14000
	v_add_u32_e32 v142, s58, v176
	v_add_u32_e32 v180, s59, v176
	ds_read_b128 v[130:133], v142
	ds_read_b128 v[134:137], v142 offset:1024
	ds_read_b128 v[138:141], v142 offset:2048
	ds_read_b128 v[142:145], v142 offset:3072
	ds_read_b128 v[146:149], v180
	ds_read_b128 v[150:153], v180 offset:1024
	ds_read_b128 v[170:173], v180 offset:2048
	ds_read_b128 v[180:183], v180 offset:3072
	s_add_u32 s38, s38, 0x100000
	s_addc_u32 s39, s39, 0
	s_mov_b32 m0, s25
	v_add_u32_e32 v212, s50, v177
	v_lshl_add_u64 v[222:223], s[38:39], 0, v[154:155]
	ds_read_b128 v[184:187], v212
	ds_read_b128 v[188:191], v212 offset:1024
	ds_read_b128 v[192:195], v212 offset:2048
	ds_read_b128 v[196:199], v212 offset:3072
	ds_read_b128 v[200:203], v212 offset:4096
	ds_read_b128 v[204:207], v212 offset:5120
	ds_read_b128 v[208:211], v212 offset:6144
	ds_read_b128 v[212:215], v212 offset:7168
	global_load_lds_dwordx4 v[222:223], off
	v_lshl_add_u64 v[222:223], s[38:39], 0, v[158:159]
	s_mov_b32 m0, s44
	s_add_i32 s38, s25, s48
	global_load_lds_dwordx4 v[222:223], off
	v_lshl_add_u64 v[174:175], v[174:175], 0, s[6:7]
	s_mov_b32 m0, s38
	s_nop 0
	global_load_lds_dwordx4 v[174:175], off
	v_lshl_add_u64 v[174:175], v[216:217], 0, s[6:7]
	s_add_i32 m0, s38, 0x2000
	s_nop 0
	global_load_lds_dwordx4 v[174:175], off
	s_waitcnt vmcnt(10)
	s_waitcnt lgkmcnt(0)
	s_barrier
; #define PG8_STAGE(bufoff, gbase, voff) do { _Pragma("unroll") for (int _i = 0; _i < 2; ++_i) \
;         __builtin_amdgcn_global_load_lds((const unsigned*)((const char*)(gbase) + (voff)[_i]), (LAS unsigned*)(lds + (bufoff) + ldsw + _i * 8192), 16, 0, 0); } while (0)
; #define PG8_LDA(dst, off) do { _Pragma("unroll") for (int m = 0; m < 4; ++m) _Pragma("unroll") for (int k = 0; k < 2; ++k) dst[m][k] = *(const LAS bf16x8*)(lds + (off) + aoff + m * 2048 + k * 1024); } while (0)
; #define PG8_MMA(ai, bj, At, Bt) do { __builtin_amdgcn_s_setprio(1); _Pragma("unroll") for (int m = 0; m < 4; ++m) _Pragma("unroll") for (int n = 0; n < 2; ++n) _Pragma("unroll") for (int k = 0; k < 2; ++k) \
;         acc[ai][bj][m][n] = __builtin_amdgcn_mfma_f32_16x16x32_bf16(Bt[n][k], At[m][k], acc[ai][bj][m][n], 0, 0, 0); __builtin_amdgcn_s_setprio(0); } while (0)
; #define PG8_WAIT_V(n) asm volatile("s_waitcnt vmcnt(" #n ")" ::: "memory")
; #define PG8_WAIT_L(n) asm volatile("s_waitcnt lgkmcnt(" #n ")" ::: "memory")
; #define PG8_BAR __builtin_amdgcn_s_barrier()
; #define PG8_SCHED __builtin_amdgcn_sched_barrier(0)
; template <class Epi, bool ALIGN_EPI = true>
; __device__ __forceinline__ void gemm_phase(LAS unsigned char* lds, const Gemm g, const StaticOrder& S, const Epi& E) {
;     ...
;             PG8_WAIT_V(10); PG8_WAIT_L(0); PG8_BAR; PG8_MMA(0, 0, At, B0); PG8_MMA(0, 1, At, B1); PG8_BAR; PG8_SCHED;
;             PG8_LDA(At, PG8_SA1(1)); PG8_STAGE(PG8_SB(1, 0), b3, voffB); PG8_STAGE(PG8_SB(1, 1), b3 + hstep, voffB);
;             PG8_WAIT_V(8); PG8_WAIT_L(0); PG8_BAR; PG8_MMA(1, 0, At, B0); PG8_MMA(1, 1, At, B1); PG8_BAR; PG8_SCHED;
;             { const int t_ = o0; o0 = o2; o2 = o1; o1 = t_; }
;         }
;         if constexpr (ALIGN_EPI) { if (wr == 0) PG8_BAR; }
	s_setprio 1
	s_waitcnt lgkmcnt(0)
	v_mfma_f32_16x16x32_bf16 v[126:129], v[130:133], v[184:187], v[126:129]
	v_mfma_f32_16x16x32_bf16 v[126:129], v[134:137], v[188:191], v[126:129]
	v_mfma_f32_16x16x32_bf16 v[122:125], v[138:141], v[184:187], v[122:125]
	v_mfma_f32_16x16x32_bf16 v[122:125], v[142:145], v[188:191], v[122:125]
	v_mfma_f32_16x16x32_bf16 v[110:113], v[146:149], v[184:187], v[110:113]
	v_mfma_f32_16x16x32_bf16 v[110:113], v[150:153], v[188:191], v[110:113]
	v_mfma_f32_16x16x32_bf16 v[106:109], v[170:173], v[184:187], v[106:109]
	v_mfma_f32_16x16x32_bf16 v[106:109], v[180:183], v[188:191], v[106:109]
	v_mfma_f32_16x16x32_bf16 v[118:121], v[130:133], v[192:195], v[118:121]
	v_mfma_f32_16x16x32_bf16 v[118:121], v[134:137], v[196:199], v[118:121]
	v_mfma_f32_16x16x32_bf16 v[114:117], v[138:141], v[192:195], v[114:117]
	v_mfma_f32_16x16x32_bf16 v[114:117], v[142:145], v[196:199], v[114:117]
	v_mfma_f32_16x16x32_bf16 v[102:105], v[146:149], v[192:195], v[102:105]
	v_mfma_f32_16x16x32_bf16 v[102:105], v[150:153], v[196:199], v[102:105]
	v_mfma_f32_16x16x32_bf16 v[98:101], v[170:173], v[192:195], v[98:101]
	v_mfma_f32_16x16x32_bf16 v[98:101], v[180:183], v[196:199], v[98:101]
	s_setprio 0
	s_setprio 1
	v_mfma_f32_16x16x32_bf16 v[94:97], v[130:133], v[200:203], v[94:97]
	v_mfma_f32_16x16x32_bf16 v[94:97], v[134:137], v[204:207], v[94:97]
	v_mfma_f32_16x16x32_bf16 v[90:93], v[138:141], v[200:203], v[90:93]
	v_mfma_f32_16x16x32_bf16 v[90:93], v[142:145], v[204:207], v[90:93]
	v_mfma_f32_16x16x32_bf16 v[86:89], v[146:149], v[200:203], v[86:89]
	v_mfma_f32_16x16x32_bf16 v[86:89], v[150:153], v[204:207], v[86:89]
	v_mfma_f32_16x16x32_bf16 v[78:81], v[170:173], v[200:203], v[78:81]
	v_mfma_f32_16x16x32_bf16 v[78:81], v[180:183], v[204:207], v[78:81]
	v_mfma_f32_16x16x32_bf16 v[82:85], v[130:133], v[208:211], v[82:85]
	v_mfma_f32_16x16x32_bf16 v[82:85], v[134:137], v[212:215], v[82:85]
	v_mfma_f32_16x16x32_bf16 v[74:77], v[138:141], v[208:211], v[74:77]
	v_mfma_f32_16x16x32_bf16 v[74:77], v[142:145], v[212:215], v[74:77]
	v_mfma_f32_16x16x32_bf16 v[70:73], v[146:149], v[208:211], v[70:73]
	v_mfma_f32_16x16x32_bf16 v[70:73], v[150:153], v[212:215], v[70:73]
	v_mfma_f32_16x16x32_bf16 v[66:69], v[170:173], v[208:211], v[66:69]
	v_mfma_f32_16x16x32_bf16 v[66:69], v[180:183], v[212:215], v[66:69]
	s_setprio 0
	s_barrier
	s_add_i32 s38, s58, s35
	v_lshl_add_u64 v[174:175], v[218:219], 0, s[6:7]
	s_mov_b32 m0, s38
	ds_read_b128 v[184:187], v177 offset:16384
	ds_read_b128 v[188:191], v177 offset:17408
	ds_read_b128 v[192:195], v177 offset:18432
	ds_read_b128 v[196:199], v177 offset:19456
	ds_read_b128 v[200:203], v177 offset:20480
	ds_read_b128 v[204:207], v177 offset:21504
	ds_read_b128 v[208:211], v177 offset:22528
	ds_read_b128 v[212:215], v177 offset:23552
	global_load_lds_dwordx4 v[174:175], off
	s_add_i32 m0, s38, 0x2000
	s_add_u32 s28, s28, 0x100080
	v_lshl_add_u64 v[174:175], v[220:221], 0, s[6:7]
	s_addc_u32 s29, s29, 0
	s_add_i32 s38, s59, s35
	global_load_lds_dwordx4 v[174:175], off
	v_lshl_add_u64 v[174:175], s[28:29], 0, v[156:157]
	s_mov_b32 m0, s38
	s_nop 0
	global_load_lds_dwordx4 v[174:175], off
	v_lshl_add_u64 v[174:175], s[28:29], 0, v[160:161]
	s_add_i32 m0, s38, 0x2000
	s_nop 0
	global_load_lds_dwordx4 v[174:175], off
	s_waitcnt vmcnt(8)
	s_waitcnt lgkmcnt(0)
	s_barrier
	s_setprio 1
	s_waitcnt lgkmcnt(0)
	v_mfma_f32_16x16x32_bf16 v[62:65], v[130:133], v[184:187], v[62:65]
	v_mfma_f32_16x16x32_bf16 v[62:65], v[134:137], v[188:191], v[62:65]
	v_mfma_f32_16x16x32_bf16 v[58:61], v[138:141], v[184:187], v[58:61]
	v_mfma_f32_16x16x32_bf16 v[58:61], v[142:145], v[188:191], v[58:61]
	v_mfma_f32_16x16x32_bf16 v[54:57], v[146:149], v[184:187], v[54:57]
	v_mfma_f32_16x16x32_bf16 v[54:57], v[150:153], v[188:191], v[54:57]
	v_mfma_f32_16x16x32_bf16 v[46:49], v[170:173], v[184:187], v[46:49]
	v_mfma_f32_16x16x32_bf16 v[46:49], v[180:183], v[188:191], v[46:49]
	v_mfma_f32_16x16x32_bf16 v[50:53], v[130:133], v[192:195], v[50:53]
	v_mfma_f32_16x16x32_bf16 v[50:53], v[134:137], v[196:199], v[50:53]
	v_mfma_f32_16x16x32_bf16 v[42:45], v[138:141], v[192:195], v[42:45]
	v_mfma_f32_16x16x32_bf16 v[42:45], v[142:145], v[196:199], v[42:45]
	v_mfma_f32_16x16x32_bf16 v[38:41], v[146:149], v[192:195], v[38:41]
	v_mfma_f32_16x16x32_bf16 v[38:41], v[150:153], v[196:199], v[38:41]
	v_mfma_f32_16x16x32_bf16 v[30:33], v[170:173], v[192:195], v[30:33]
	v_mfma_f32_16x16x32_bf16 v[30:33], v[180:183], v[196:199], v[30:33]
	s_setprio 0
	s_setprio 1
	v_mfma_f32_16x16x32_bf16 v[34:37], v[130:133], v[200:203], v[34:37]
	v_mfma_f32_16x16x32_bf16 v[34:37], v[134:137], v[204:207], v[34:37]
	v_mfma_f32_16x16x32_bf16 v[26:29], v[138:141], v[200:203], v[26:29]
	v_mfma_f32_16x16x32_bf16 v[26:29], v[142:145], v[204:207], v[26:29]
	v_mfma_f32_16x16x32_bf16 v[22:25], v[146:149], v[200:203], v[22:25]
	v_mfma_f32_16x16x32_bf16 v[22:25], v[150:153], v[204:207], v[22:25]
	v_mfma_f32_16x16x32_bf16 v[14:17], v[170:173], v[200:203], v[14:17]
	v_mfma_f32_16x16x32_bf16 v[14:17], v[180:183], v[204:207], v[14:17]
	v_mfma_f32_16x16x32_bf16 v[18:21], v[130:133], v[208:211], v[18:21]
	v_mfma_f32_16x16x32_bf16 v[18:21], v[134:137], v[212:215], v[18:21]
	v_mfma_f32_16x16x32_bf16 v[10:13], v[138:141], v[208:211], v[10:13]
	v_mfma_f32_16x16x32_bf16 v[10:13], v[142:145], v[212:215], v[10:13]
	v_mfma_f32_16x16x32_bf16 v[6:9], v[146:149], v[208:211], v[6:9]
	v_mfma_f32_16x16x32_bf16 v[6:9], v[150:153], v[212:215], v[6:9]
	v_mfma_f32_16x16x32_bf16 v[2:5], v[170:173], v[208:211], v[2:5]
	v_mfma_f32_16x16x32_bf16 v[2:5], v[180:183], v[212:215], v[2:5]
	s_setprio 0
	s_barrier
	s_add_i32 s57, s57, 2
	s_add_u32 s26, s26, 0x100
	s_addc_u32 s27, s27, 0
	s_add_u32 s55, s55, 0x100
	s_addc_u32 s56, s56, 0
	s_cmp_gt_u32 s57, 61
	s_mov_b32 s28, s51
	s_cbranch_scc0 .LBB0_772
	s_and_b64 vcc, exec, s[8:9]
	s_cbranch_vccz .LBB0_775
	s_barrier

; #define PG8_STAGE(bufoff, gbase, voff) do { _Pragma("unroll") for (int _i = 0; _i < 2; ++_i) \
;         __builtin_amdgcn_global_load_lds((const unsigned*)((const char*)(gbase) + (voff)[_i]), (LAS unsigned*)(lds + (bufoff) + ldsw + _i * 8192), 16, 0, 0); } while (0)
; #define PG8_LDA(dst, off) do { _Pragma("unroll") for (int m = 0; m < 4; ++m) _Pragma("unroll") for (int k = 0; k < 2; ++k) dst[m][k] = *(const LAS bf16x8*)(lds + (off) + aoff + m * 2048 + k * 1024); } while (0)
; #define PG8_LDB(dst, b, h) do { _Pragma("unroll") for (int n = 0; n < 2; ++n) _Pragma("unroll") for (int k = 0; k < 2; ++k) dst[n][k] = *(const LAS bf16x8*)(lds + PG8_SB(b, h) + boff + n * 2048 + k * 1024); } while (0)
; #define PG8_MMA(ai, bj, At, Bt) do { __builtin_amdgcn_s_setprio(1); _Pragma("unroll") for (int m = 0; m < 4; ++m) _Pragma("unroll") for (int n = 0; n < 2; ++n) _Pragma("unroll") for (int k = 0; k < 2; ++k) \
;         acc[ai][bj][m][n] = __builtin_amdgcn_mfma_f32_16x16x32_bf16(Bt[n][k], At[m][k], acc[ai][bj][m][n], 0, 0, 0); __builtin_amdgcn_s_setprio(0); } while (0)
; #define PG8_WAIT_V(n) asm volatile("s_waitcnt vmcnt(" #n ")" ::: "memory")
; #define PG8_WAIT_L(n) asm volatile("s_waitcnt lgkmcnt(" #n ")" ::: "memory")
; #define PG8_BAR __builtin_amdgcn_s_barrier()
; #define PG8_SCHED __builtin_amdgcn_sched_barrier(0)
; template <class Epi, bool ALIGN_EPI = true>
; __device__ __forceinline__ void gemm_phase(LAS unsigned char* lds, const Gemm g, const StaticOrder& S, const Epi& E) {
;     ...
;             const bool last = (t == nt - 2);
;             const char* a1 = cA + (size_t)(t + 1) * kstep;
;             const char* a2 = last ? nA : cA + (size_t)(t + 2) * kstep; const char* b2 = last ? nB : cB + (size_t)(t + 2) * kstep;
;             const char* a3 = a2 + kstep; const char* b3 = b2 + kstep;
;             PG8_LDB(B0, 0, 0); PG8_LDB(B1, 0, 1); PG8_SCHED; PG8_LDA(At, o0); PG8_STAGE(PG8_SA1(1), a1 + hstep, voffA); PG8_STAGE(o2, a2, voffA);
;             PG8_WAIT_V(10); PG8_WAIT_L(0); PG8_BAR; PG8_MMA(0, 0, At, B0); PG8_MMA(0, 1, At, B1); PG8_BAR; PG8_SCHED;
;             PG8_LDA(At, PG8_SA1(0)); PG8_STAGE(PG8_SB(0, 0), b2, voffB); PG8_STAGE(PG8_SB(0, 1), b2 + hstep, voffB);
;             PG8_WAIT_V(8); PG8_WAIT_L(0); PG8_BAR; PG8_MMA(1, 0, At, B0); PG8_MMA(1, 1, At, B1); PG8_BAR; PG8_SCHED;
.LBB0_903:
	ds_read_b128 v[110:113], v218 offset:32768
	ds_read_b128 v[114:117], v218 offset:33792
	ds_read_b128 v[118:121], v218 offset:34816
	ds_read_b128 v[126:129], v218 offset:35840
	ds_read_b128 v[130:133], v218 offset:49152
	ds_read_b128 v[134:137], v218 offset:50176
	ds_read_b128 v[138:141], v218 offset:51200
	ds_read_b128 v[142:145], v218 offset:52224
	s_mov_b32 s73, s69
	s_mov_b32 s69, s66
	s_mov_b32 s66, s54
	s_add_u32 s54, s52, 0xfff00080
	s_addc_u32 s55, s53, -1
	s_cmp_eq_u32 s75, 60
	s_cselect_b32 s56, s13, s54
	s_cselect_b32 s54, s45, s47
	s_cselect_b32 s57, s11, s55
	s_cselect_b32 s55, s33, s74
	v_add_u32_e32 v210, s66, v216
	v_lshl_add_u64 v[214:215], s[52:53], 0, v[174:175]
	s_add_i32 m0, s59, 0x4000
	ds_read_b128 v[182:185], v210
	ds_read_b128 v[186:189], v210 offset:1024
	ds_read_b128 v[190:193], v210 offset:2048
	ds_read_b128 v[194:197], v210 offset:3072
	ds_read_b128 v[198:201], v210 offset:4096
	ds_read_b128 v[202:205], v210 offset:5120
	ds_read_b128 v[206:209], v210 offset:6144
	ds_read_b128 v[210:213], v210 offset:7168
	global_load_lds_dwordx4 v[214:215], off
	v_lshl_add_u64 v[214:215], s[52:53], 0, v[176:177]
	s_add_i32 m0, s59, 0x6000
	s_add_i32 s76, s59, s73
	global_load_lds_dwordx4 v[214:215], off
	v_lshl_add_u64 v[214:215], s[56:57], 0, v[162:163]
	s_mov_b32 m0, s76
	v_lshl_add_u64 v[220:221], s[56:57], 0, v[166:167]
	global_load_lds_dwordx4 v[214:215], off
	s_add_i32 m0, s76, 0x2000
	s_nop 0
	global_load_lds_dwordx4 v[220:221], off
	s_waitcnt vmcnt(10)
	s_waitcnt lgkmcnt(0)
	s_barrier
	s_setprio 1
	s_waitcnt lgkmcnt(0)
	v_mfma_f32_16x16x32_bf16 v[158:161], v[110:113], v[182:185], v[158:161]
	v_mfma_f32_16x16x32_bf16 v[158:161], v[114:117], v[186:189], v[158:161]
	v_mfma_f32_16x16x32_bf16 v[62:65], v[118:121], v[182:185], v[62:65]
	v_mfma_f32_16x16x32_bf16 v[62:65], v[126:129], v[186:189], v[62:65]
	v_mfma_f32_16x16x32_bf16 v[154:157], v[130:133], v[182:185], v[154:157]
	v_mfma_f32_16x16x32_bf16 v[154:157], v[134:137], v[186:189], v[154:157]
	v_mfma_f32_16x16x32_bf16 v[58:61], v[138:141], v[182:185], v[58:61]
	v_mfma_f32_16x16x32_bf16 v[58:61], v[142:145], v[186:189], v[58:61]
	v_mfma_f32_16x16x32_bf16 v[150:153], v[110:113], v[190:193], v[150:153]
	v_mfma_f32_16x16x32_bf16 v[150:153], v[114:117], v[194:197], v[150:153]
	v_mfma_f32_16x16x32_bf16 v[54:57], v[118:121], v[190:193], v[54:57]
	v_mfma_f32_16x16x32_bf16 v[54:57], v[126:129], v[194:197], v[54:57]
	v_mfma_f32_16x16x32_bf16 v[146:149], v[130:133], v[190:193], v[146:149]
	v_mfma_f32_16x16x32_bf16 v[146:149], v[134:137], v[194:197], v[146:149]
	v_mfma_f32_16x16x32_bf16 v[50:53], v[138:141], v[190:193], v[50:53]
	v_mfma_f32_16x16x32_bf16 v[50:53], v[142:145], v[194:197], v[50:53]
	s_setprio 0
	s_setprio 1
	v_mfma_f32_16x16x32_bf16 v[122:125], v[110:113], v[198:201], v[122:125]
	v_mfma_f32_16x16x32_bf16 v[122:125], v[114:117], v[202:205], v[122:125]
	v_mfma_f32_16x16x32_bf16 v[46:49], v[118:121], v[198:201], v[46:49]
	v_mfma_f32_16x16x32_bf16 v[46:49], v[126:129], v[202:205], v[46:49]
	v_mfma_f32_16x16x32_bf16 v[106:109], v[130:133], v[198:201], v[106:109]
	v_mfma_f32_16x16x32_bf16 v[106:109], v[134:137], v[202:205], v[106:109]
	v_mfma_f32_16x16x32_bf16 v[42:45], v[138:141], v[198:201], v[42:45]
	v_mfma_f32_16x16x32_bf16 v[42:45], v[142:145], v[202:205], v[42:45]
	v_mfma_f32_16x16x32_bf16 v[102:105], v[110:113], v[206:209], v[102:105]
	v_mfma_f32_16x16x32_bf16 v[102:105], v[114:117], v[210:213], v[102:105]
	v_mfma_f32_16x16x32_bf16 v[38:41], v[118:121], v[206:209], v[38:41]
	v_mfma_f32_16x16x32_bf16 v[38:41], v[126:129], v[210:213], v[38:41]
	v_mfma_f32_16x16x32_bf16 v[98:101], v[130:133], v[206:209], v[98:101]
	v_mfma_f32_16x16x32_bf16 v[98:101], v[134:137], v[210:213], v[98:101]
	v_mfma_f32_16x16x32_bf16 v[34:37], v[138:141], v[206:209], v[34:37]
	v_mfma_f32_16x16x32_bf16 v[34:37], v[142:145], v[210:213], v[34:37]
	s_setprio 0
	s_barrier
	s_mov_b32 m0, s60
	v_lshl_add_u64 v[222:223], s[54:55], 0, v[164:165]
	s_add_u32 s76, s54, 0x100000
	ds_read_b128 v[182:185], v216
	ds_read_b128 v[186:189], v216 offset:1024
	ds_read_b128 v[190:193], v216 offset:2048
	ds_read_b128 v[194:197], v216 offset:3072
	ds_read_b128 v[198:201], v216 offset:4096
	ds_read_b128 v[202:205], v216 offset:5120
	ds_read_b128 v[206:209], v216 offset:6144
	ds_read_b128 v[210:213], v216 offset:7168
	global_load_lds_dwordx4 v[222:223], off
	v_lshl_add_u64 v[224:225], s[54:55], 0, v[168:169]
	s_mov_b32 m0, s61
	s_addc_u32 s77, s55, 0
	global_load_lds_dwordx4 v[224:225], off
	v_lshl_add_u64 v[226:227], s[76:77], 0, v[164:165]
	s_mov_b32 m0, s62
	s_nop 0
	global_load_lds_dwordx4 v[226:227], off
	v_lshl_add_u64 v[226:227], s[76:77], 0, v[168:169]
	s_mov_b32 m0, s63
	s_nop 0
	global_load_lds_dwordx4 v[226:227], off
	s_waitcnt vmcnt(8)
	s_waitcnt lgkmcnt(0)
	s_barrier
; #define PG8_STAGE(bufoff, gbase, voff) do { _Pragma("unroll") for (int _i = 0; _i < 2; ++_i) \
;         __builtin_amdgcn_global_load_lds((const unsigned*)((const char*)(gbase) + (voff)[_i]), (LAS unsigned*)(lds + (bufoff) + ldsw + _i * 8192), 16, 0, 0); } while (0)
; #define PG8_LDA(dst, off) do { _Pragma("unroll") for (int m = 0; m < 4; ++m) _Pragma("unroll") for (int k = 0; k < 2; ++k) dst[m][k] = *(const LAS bf16x8*)(lds + (off) + aoff + m * 2048 + k * 1024); } while (0)
; #define PG8_LDB(dst, b, h) do { _Pragma("unroll") for (int n = 0; n < 2; ++n) _Pragma("unroll") for (int k = 0; k < 2; ++k) dst[n][k] = *(const LAS bf16x8*)(lds + PG8_SB(b, h) + boff + n * 2048 + k * 1024); } while (0)
; #define PG8_MMA(ai, bj, At, Bt) do { __builtin_amdgcn_s_setprio(1); _Pragma("unroll") for (int m = 0; m < 4; ++m) _Pragma("unroll") for (int n = 0; n < 2; ++n) _Pragma("unroll") for (int k = 0; k < 2; ++k) \
;         acc[ai][bj][m][n] = __builtin_amdgcn_mfma_f32_16x16x32_bf16(Bt[n][k], At[m][k], acc[ai][bj][m][n], 0, 0, 0); __builtin_amdgcn_s_setprio(0); } while (0)
; #define PG8_WAIT_V(n) asm volatile("s_waitcnt vmcnt(" #n ")" ::: "memory")
; #define PG8_WAIT_L(n) asm volatile("s_waitcnt lgkmcnt(" #n ")" ::: "memory")
; #define PG8_BAR __builtin_amdgcn_s_barrier()
; #define PG8_SCHED __builtin_amdgcn_sched_barrier(0)
; template <class Epi, bool ALIGN_EPI = true>
; __device__ __forceinline__ void gemm_phase(LAS unsigned char* lds, const Gemm g, const StaticOrder& S, const Epi& E) {
;     ...
;             PG8_WAIT_V(8); PG8_WAIT_L(0); PG8_BAR; PG8_MMA(1, 0, At, B0); PG8_MMA(1, 1, At, B1); PG8_BAR; PG8_SCHED;
;             PG8_LDB(B0, 1, 0); PG8_LDB(B1, 1, 1); PG8_SCHED; PG8_LDA(At, o1); PG8_STAGE(PG8_SA1(0), a2 + hstep, voffA); PG8_STAGE(o0, a3, voffA);
;             PG8_WAIT_V(10); PG8_WAIT_L(0); PG8_BAR; PG8_MMA(0, 0, At, B0); PG8_MMA(0, 1, At, B1); PG8_BAR; PG8_SCHED;
	s_setprio 1
	s_waitcnt lgkmcnt(0)
	v_mfma_f32_16x16x32_bf16 v[94:97], v[110:113], v[182:185], v[94:97]
	v_mfma_f32_16x16x32_bf16 v[94:97], v[114:117], v[186:189], v[94:97]
	v_mfma_f32_16x16x32_bf16 v[30:33], v[118:121], v[182:185], v[30:33]
	v_mfma_f32_16x16x32_bf16 v[30:33], v[126:129], v[186:189], v[30:33]
	v_mfma_f32_16x16x32_bf16 v[90:93], v[130:133], v[182:185], v[90:93]
	v_mfma_f32_16x16x32_bf16 v[90:93], v[134:137], v[186:189], v[90:93]
	v_mfma_f32_16x16x32_bf16 v[26:29], v[138:141], v[182:185], v[26:29]
	v_mfma_f32_16x16x32_bf16 v[26:29], v[142:145], v[186:189], v[26:29]
	v_mfma_f32_16x16x32_bf16 v[86:89], v[110:113], v[190:193], v[86:89]
	v_mfma_f32_16x16x32_bf16 v[86:89], v[114:117], v[194:197], v[86:89]
	v_mfma_f32_16x16x32_bf16 v[22:25], v[118:121], v[190:193], v[22:25]
	v_mfma_f32_16x16x32_bf16 v[22:25], v[126:129], v[194:197], v[22:25]
	v_mfma_f32_16x16x32_bf16 v[82:85], v[130:133], v[190:193], v[82:85]
	v_mfma_f32_16x16x32_bf16 v[82:85], v[134:137], v[194:197], v[82:85]
	v_mfma_f32_16x16x32_bf16 v[18:21], v[138:141], v[190:193], v[18:21]
	v_mfma_f32_16x16x32_bf16 v[18:21], v[142:145], v[194:197], v[18:21]
	s_setprio 0
	s_setprio 1
	v_mfma_f32_16x16x32_bf16 v[78:81], v[110:113], v[198:201], v[78:81]
	v_mfma_f32_16x16x32_bf16 v[78:81], v[114:117], v[202:205], v[78:81]
	v_mfma_f32_16x16x32_bf16 v[14:17], v[118:121], v[198:201], v[14:17]
	v_mfma_f32_16x16x32_bf16 v[14:17], v[126:129], v[202:205], v[14:17]
	v_mfma_f32_16x16x32_bf16 v[74:77], v[130:133], v[198:201], v[74:77]
	v_mfma_f32_16x16x32_bf16 v[74:77], v[134:137], v[202:205], v[74:77]
	v_mfma_f32_16x16x32_bf16 v[10:13], v[138:141], v[198:201], v[10:13]
	v_mfma_f32_16x16x32_bf16 v[10:13], v[142:145], v[202:205], v[10:13]
	v_mfma_f32_16x16x32_bf16 v[70:73], v[110:113], v[206:209], v[70:73]
	v_mfma_f32_16x16x32_bf16 v[70:73], v[114:117], v[210:213], v[70:73]
	v_mfma_f32_16x16x32_bf16 v[6:9], v[118:121], v[206:209], v[6:9]
	v_mfma_f32_16x16x32_bf16 v[6:9], v[126:129], v[210:213], v[6:9]
	v_mfma_f32_16x16x32_bf16 v[66:69], v[130:133], v[206:209], v[66:69]
	v_mfma_f32_16x16x32_bf16 v[66:69], v[134:137], v[210:213], v[66:69]
	v_mfma_f32_16x16x32_bf16 v[2:5], v[138:141], v[206:209], v[2:5]
	v_mfma_f32_16x16x32_bf16 v[2:5], v[142:145], v[210:213], v[2:5]
	s_setprio 0
	s_barrier
	s_add_i32 s76, 0, 0x10000
	s_add_i32 s77, 0, 0x14000
	v_add_u32_e32 v126, s76, v171
	v_add_u32_e32 v142, s77, v171
	ds_read_b128 v[110:113], v126
	ds_read_b128 v[114:117], v126 offset:1024
	ds_read_b128 v[118:121], v126 offset:2048
	ds_read_b128 v[126:129], v126 offset:3072
	ds_read_b128 v[130:133], v142
	ds_read_b128 v[134:137], v142 offset:1024
	ds_read_b128 v[138:141], v142 offset:2048
	ds_read_b128 v[142:145], v142 offset:3072
	s_add_u32 s56, s56, 0x100000
	s_addc_u32 s57, s57, 0
	s_mov_b32 m0, s59
	v_add_u32_e32 v210, s69, v216
	v_lshl_add_u64 v[226:227], s[56:57], 0, v[162:163]
	ds_read_b128 v[182:185], v210
	ds_read_b128 v[186:189], v210 offset:1024
	ds_read_b128 v[190:193], v210 offset:2048
	ds_read_b128 v[194:197], v210 offset:3072
	ds_read_b128 v[198:201], v210 offset:4096
	ds_read_b128 v[202:205], v210 offset:5120
	ds_read_b128 v[206:209], v210 offset:6144
	ds_read_b128 v[210:213], v210 offset:7168
	global_load_lds_dwordx4 v[226:227], off
	v_lshl_add_u64 v[226:227], s[56:57], 0, v[166:167]
	s_mov_b32 m0, s64
	s_add_i32 s56, s59, s66
	global_load_lds_dwordx4 v[226:227], off
	v_lshl_add_u64 v[214:215], v[214:215], 0, s[24:25]
	s_mov_b32 m0, s56
	s_nop 0
	global_load_lds_dwordx4 v[214:215], off
	v_lshl_add_u64 v[214:215], v[220:221], 0, s[24:25]
	s_add_i32 m0, s56, 0x2000
	s_nop 0
	global_load_lds_dwordx4 v[214:215], off
	s_waitcnt vmcnt(10)
	s_waitcnt lgkmcnt(0)
	s_barrier
; #define PG8_STAGE(bufoff, gbase, voff) do { _Pragma("unroll") for (int _i = 0; _i < 2; ++_i) \
;         __builtin_amdgcn_global_load_lds((const unsigned*)((const char*)(gbase) + (voff)[_i]), (LAS unsigned*)(lds + (bufoff) + ldsw + _i * 8192), 16, 0, 0); } while (0)
; #define PG8_LDA(dst, off) do { _Pragma("unroll") for (int m = 0; m < 4; ++m) _Pragma("unroll") for (int k = 0; k < 2; ++k) dst[m][k] = *(const LAS bf16x8*)(lds + (off) + aoff + m * 2048 + k * 1024); } while (0)
; #define PG8_MMA(ai, bj, At, Bt) do { __builtin_amdgcn_s_setprio(1); _Pragma("unroll") for (int m = 0; m < 4; ++m) _Pragma("unroll") for (int n = 0; n < 2; ++n) _Pragma("unroll") for (int k = 0; k < 2; ++k) \
;         acc[ai][bj][m][n] = __builtin_amdgcn_mfma_f32_16x16x32_bf16(Bt[n][k], At[m][k], acc[ai][bj][m][n], 0, 0, 0); __builtin_amdgcn_s_setprio(0); } while (0)
; #define PG8_WAIT_V(n) asm volatile("s_waitcnt vmcnt(" #n ")" ::: "memory")
; #define PG8_WAIT_L(n) asm volatile("s_waitcnt lgkmcnt(" #n ")" ::: "memory")
; #define PG8_BAR __builtin_amdgcn_s_barrier()
; #define PG8_SCHED __builtin_amdgcn_sched_barrier(0)
; template <class Epi, bool ALIGN_EPI = true>
; __device__ __forceinline__ void gemm_phase(LAS unsigned char* lds, const Gemm g, const StaticOrder& S, const Epi& E) {
;     ...
;             PG8_WAIT_V(10); PG8_WAIT_L(0); PG8_BAR; PG8_MMA(0, 0, At, B0); PG8_MMA(0, 1, At, B1); PG8_BAR; PG8_SCHED;
;             PG8_LDA(At, PG8_SA1(1)); PG8_STAGE(PG8_SB(1, 0), b3, voffB); PG8_STAGE(PG8_SB(1, 1), b3 + hstep, voffB);
;             PG8_WAIT_V(8); PG8_WAIT_L(0); PG8_BAR; PG8_MMA(1, 0, At, B0); PG8_MMA(1, 1, At, B1); PG8_BAR; PG8_SCHED;
;             { const int t_ = o0; o0 = o2; o2 = o1; o1 = t_; }
;         }
;         if constexpr (ALIGN_EPI) { if (wr == 0) PG8_BAR; }
	s_setprio 1
	s_waitcnt lgkmcnt(0)
	v_mfma_f32_16x16x32_bf16 v[158:161], v[110:113], v[182:185], v[158:161]
	v_mfma_f32_16x16x32_bf16 v[158:161], v[114:117], v[186:189], v[158:161]
	v_mfma_f32_16x16x32_bf16 v[62:65], v[118:121], v[182:185], v[62:65]
	v_mfma_f32_16x16x32_bf16 v[62:65], v[126:129], v[186:189], v[62:65]
	v_mfma_f32_16x16x32_bf16 v[154:157], v[130:133], v[182:185], v[154:157]
	v_mfma_f32_16x16x32_bf16 v[154:157], v[134:137], v[186:189], v[154:157]
	v_mfma_f32_16x16x32_bf16 v[58:61], v[138:141], v[182:185], v[58:61]
	v_mfma_f32_16x16x32_bf16 v[58:61], v[142:145], v[186:189], v[58:61]
	v_mfma_f32_16x16x32_bf16 v[150:153], v[110:113], v[190:193], v[150:153]
	v_mfma_f32_16x16x32_bf16 v[150:153], v[114:117], v[194:197], v[150:153]
	v_mfma_f32_16x16x32_bf16 v[54:57], v[118:121], v[190:193], v[54:57]
	v_mfma_f32_16x16x32_bf16 v[54:57], v[126:129], v[194:197], v[54:57]
	v_mfma_f32_16x16x32_bf16 v[146:149], v[130:133], v[190:193], v[146:149]
	v_mfma_f32_16x16x32_bf16 v[146:149], v[134:137], v[194:197], v[146:149]
	v_mfma_f32_16x16x32_bf16 v[50:53], v[138:141], v[190:193], v[50:53]
	v_mfma_f32_16x16x32_bf16 v[50:53], v[142:145], v[194:197], v[50:53]
	s_setprio 0
	s_setprio 1
	v_mfma_f32_16x16x32_bf16 v[122:125], v[110:113], v[198:201], v[122:125]
	v_mfma_f32_16x16x32_bf16 v[122:125], v[114:117], v[202:205], v[122:125]
	v_mfma_f32_16x16x32_bf16 v[46:49], v[118:121], v[198:201], v[46:49]
	v_mfma_f32_16x16x32_bf16 v[46:49], v[126:129], v[202:205], v[46:49]
	v_mfma_f32_16x16x32_bf16 v[106:109], v[130:133], v[198:201], v[106:109]
	v_mfma_f32_16x16x32_bf16 v[106:109], v[134:137], v[202:205], v[106:109]
	v_mfma_f32_16x16x32_bf16 v[42:45], v[138:141], v[198:201], v[42:45]
	v_mfma_f32_16x16x32_bf16 v[42:45], v[142:145], v[202:205], v[42:45]
	v_mfma_f32_16x16x32_bf16 v[102:105], v[110:113], v[206:209], v[102:105]
	v_mfma_f32_16x16x32_bf16 v[102:105], v[114:117], v[210:213], v[102:105]
	v_mfma_f32_16x16x32_bf16 v[38:41], v[118:121], v[206:209], v[38:41]
	v_mfma_f32_16x16x32_bf16 v[38:41], v[126:129], v[210:213], v[38:41]
	v_mfma_f32_16x16x32_bf16 v[98:101], v[130:133], v[206:209], v[98:101]
	v_mfma_f32_16x16x32_bf16 v[98:101], v[134:137], v[210:213], v[98:101]
	v_mfma_f32_16x16x32_bf16 v[34:37], v[138:141], v[206:209], v[34:37]
	v_mfma_f32_16x16x32_bf16 v[34:37], v[142:145], v[210:213], v[34:37]
	s_setprio 0
	s_barrier
	s_add_i32 s56, s76, s58
	v_lshl_add_u64 v[214:215], v[222:223], 0, s[24:25]
	s_mov_b32 m0, s56
	ds_read_b128 v[182:185], v216 offset:16384
	ds_read_b128 v[186:189], v216 offset:17408
	ds_read_b128 v[190:193], v216 offset:18432
	ds_read_b128 v[194:197], v216 offset:19456
	ds_read_b128 v[198:201], v216 offset:20480
	ds_read_b128 v[202:205], v216 offset:21504
	ds_read_b128 v[206:209], v216 offset:22528
	ds_read_b128 v[210:213], v216 offset:23552
	global_load_lds_dwordx4 v[214:215], off
	s_add_i32 m0, s56, 0x2000
	s_add_u32 s54, s54, 0x100080
	v_lshl_add_u64 v[214:215], v[224:225], 0, s[24:25]
	s_addc_u32 s55, s55, 0
	s_add_i32 s56, s77, s58
	global_load_lds_dwordx4 v[214:215], off
	v_lshl_add_u64 v[214:215], s[54:55], 0, v[164:165]
	s_mov_b32 m0, s56
	s_nop 0
	global_load_lds_dwordx4 v[214:215], off
	v_lshl_add_u64 v[214:215], s[54:55], 0, v[168:169]
	s_add_i32 m0, s56, 0x2000
	s_nop 0
	global_load_lds_dwordx4 v[214:215], off
	s_waitcnt vmcnt(8)
	s_waitcnt lgkmcnt(0)
	s_barrier
	s_setprio 1
	s_waitcnt lgkmcnt(0)
	v_mfma_f32_16x16x32_bf16 v[94:97], v[110:113], v[182:185], v[94:97]
	v_mfma_f32_16x16x32_bf16 v[94:97], v[114:117], v[186:189], v[94:97]
	v_mfma_f32_16x16x32_bf16 v[30:33], v[118:121], v[182:185], v[30:33]
	v_mfma_f32_16x16x32_bf16 v[30:33], v[126:129], v[186:189], v[30:33]
	v_mfma_f32_16x16x32_bf16 v[90:93], v[130:133], v[182:185], v[90:93]
	v_mfma_f32_16x16x32_bf16 v[90:93], v[134:137], v[186:189], v[90:93]
	v_mfma_f32_16x16x32_bf16 v[26:29], v[138:141], v[182:185], v[26:29]
	v_mfma_f32_16x16x32_bf16 v[26:29], v[142:145], v[186:189], v[26:29]
	v_mfma_f32_16x16x32_bf16 v[86:89], v[110:113], v[190:193], v[86:89]
	v_mfma_f32_16x16x32_bf16 v[86:89], v[114:117], v[194:197], v[86:89]
	v_mfma_f32_16x16x32_bf16 v[22:25], v[118:121], v[190:193], v[22:25]
	v_mfma_f32_16x16x32_bf16 v[22:25], v[126:129], v[194:197], v[22:25]
	v_mfma_f32_16x16x32_bf16 v[82:85], v[130:133], v[190:193], v[82:85]
	v_mfma_f32_16x16x32_bf16 v[82:85], v[134:137], v[194:197], v[82:85]
	v_mfma_f32_16x16x32_bf16 v[18:21], v[138:141], v[190:193], v[18:21]
	v_mfma_f32_16x16x32_bf16 v[18:21], v[142:145], v[194:197], v[18:21]
	s_setprio 0
	s_setprio 1
	v_mfma_f32_16x16x32_bf16 v[78:81], v[110:113], v[198:201], v[78:81]
	v_mfma_f32_16x16x32_bf16 v[78:81], v[114:117], v[202:205], v[78:81]
	v_mfma_f32_16x16x32_bf16 v[14:17], v[118:121], v[198:201], v[14:17]
	v_mfma_f32_16x16x32_bf16 v[14:17], v[126:129], v[202:205], v[14:17]
	v_mfma_f32_16x16x32_bf16 v[74:77], v[130:133], v[198:201], v[74:77]
	v_mfma_f32_16x16x32_bf16 v[74:77], v[134:137], v[202:205], v[74:77]
	v_mfma_f32_16x16x32_bf16 v[10:13], v[138:141], v[198:201], v[10:13]
	v_mfma_f32_16x16x32_bf16 v[10:13], v[142:145], v[202:205], v[10:13]
	v_mfma_f32_16x16x32_bf16 v[70:73], v[110:113], v[206:209], v[70:73]
	v_mfma_f32_16x16x32_bf16 v[70:73], v[114:117], v[210:213], v[70:73]
	v_mfma_f32_16x16x32_bf16 v[6:9], v[118:121], v[206:209], v[6:9]
	v_mfma_f32_16x16x32_bf16 v[6:9], v[126:129], v[210:213], v[6:9]
	v_mfma_f32_16x16x32_bf16 v[66:69], v[130:133], v[206:209], v[66:69]
	v_mfma_f32_16x16x32_bf16 v[66:69], v[134:137], v[210:213], v[66:69]
	v_mfma_f32_16x16x32_bf16 v[2:5], v[138:141], v[206:209], v[2:5]
	v_mfma_f32_16x16x32_bf16 v[2:5], v[142:145], v[210:213], v[2:5]
	s_setprio 0
	s_barrier
	s_add_i32 s75, s75, 2
	s_add_u32 s52, s52, 0x100
	s_addc_u32 s53, s53, 0
	s_add_u32 s47, s47, 0x100
	s_addc_u32 s74, s74, 0
	s_cmp_gt_u32 s75, 61
	s_mov_b32 s54, s73
	s_cbranch_scc0 .LBB0_903
	s_and_b64 vcc, exec, s[26:27]
	s_cbranch_vccz .LBB0_906
	s_barrier

; #define PG8_STAGE(bufoff, gbase, voff) do { _Pragma("unroll") for (int _i = 0; _i < 2; ++_i) \
;         __builtin_amdgcn_global_load_lds((const unsigned*)((const char*)(gbase) + (voff)[_i]), (LAS unsigned*)(lds + (bufoff) + ldsw + _i * 8192), 16, 0, 0); } while (0)
; #define PG8_LDA(dst, off) do { _Pragma("unroll") for (int m = 0; m < 4; ++m) _Pragma("unroll") for (int k = 0; k < 2; ++k) dst[m][k] = *(const LAS bf16x8*)(lds + (off) + aoff + m * 2048 + k * 1024); } while (0)
; #define PG8_LDB(dst, b, h) do { _Pragma("unroll") for (int n = 0; n < 2; ++n) _Pragma("unroll") for (int k = 0; k < 2; ++k) dst[n][k] = *(const LAS bf16x8*)(lds + PG8_SB(b, h) + boff + n * 2048 + k * 1024); } while (0)
; #define PG8_MMA(ai, bj, At, Bt) do { __builtin_amdgcn_s_setprio(1); _Pragma("unroll") for (int m = 0; m < 4; ++m) _Pragma("unroll") for (int n = 0; n < 2; ++n) _Pragma("unroll") for (int k = 0; k < 2; ++k) \
;         acc[ai][bj][m][n] = __builtin_amdgcn_mfma_f32_16x16x32_bf16(Bt[n][k], At[m][k], acc[ai][bj][m][n], 0, 0, 0); __builtin_amdgcn_s_setprio(0); } while (0)
; #define PG8_WAIT_V(n) asm volatile("s_waitcnt vmcnt(" #n ")" ::: "memory")
; #define PG8_WAIT_L(n) asm volatile("s_waitcnt lgkmcnt(" #n ")" ::: "memory")
; #define PG8_BAR __builtin_amdgcn_s_barrier()
; #define PG8_SCHED __builtin_amdgcn_sched_barrier(0)
; template <class Epi, bool ALIGN_EPI = true>
; __device__ __forceinline__ void gemm_phase(LAS unsigned char* lds, const Gemm g, const StaticOrder& S, const Epi& E) {
;     ...
;             const bool last = (t == nt - 2);
;             const char* a1 = cA + (size_t)(t + 1) * kstep;
;             const char* a2 = last ? nA : cA + (size_t)(t + 2) * kstep; const char* b2 = last ? nB : cB + (size_t)(t + 2) * kstep;
;             const char* a3 = a2 + kstep; const char* b3 = b2 + kstep;
;             PG8_LDB(B0, 0, 0); PG8_LDB(B1, 0, 1); PG8_SCHED; PG8_LDA(At, o0); PG8_STAGE(PG8_SA1(1), a1 + hstep, voffA); PG8_STAGE(o2, a2, voffA);
;             PG8_WAIT_V(10); PG8_WAIT_L(0); PG8_BAR; PG8_MMA(0, 0, At, B0); PG8_MMA(0, 1, At, B1); PG8_BAR; PG8_SCHED;
;             PG8_LDA(At, PG8_SA1(0)); PG8_STAGE(PG8_SB(0, 0), b2, voffB); PG8_STAGE(PG8_SB(0, 1), b2 + hstep, voffB);
;             PG8_WAIT_V(8); PG8_WAIT_L(0); PG8_BAR; PG8_MMA(1, 0, At, B0); PG8_MMA(1, 1, At, B1); PG8_BAR; PG8_SCHED;
.LBB0_1077:
	ds_read_b128 v[120:123], v241 offset:32768
	ds_read_b128 v[124:127], v241 offset:33792
	ds_read_b128 v[128:131], v241 offset:34816
	ds_read_b128 v[132:135], v241 offset:35840
	ds_read_b128 v[144:147], v241 offset:49152
	ds_read_b128 v[148:151], v241 offset:50176
	ds_read_b128 v[152:155], v241 offset:51200
	ds_read_b128 v[156:159], v241 offset:52224
	s_mov_b32 s52, s49
	s_mov_b32 s49, s47
	s_mov_b32 s47, s30
	s_add_u32 s30, s28, 0xffd50080
	s_addc_u32 s31, s29, -1
	s_cmpk_eq_i32 s57, 0xa8
	s_cselect_b32 s36, s4, s30
	s_cselect_b32 s30, s26, s55
	s_cselect_b32 s37, s5, s31
	s_cselect_b32 s31, s27, s56
	v_add_u32_e32 v188, s47, v239
	v_lshl_add_u64 v[192:193], s[28:29], 0, v[212:213]
	s_add_i32 m0, s38, 0x4000
	ds_read_b128 v[160:163], v188
	ds_read_b128 v[164:167], v188 offset:1024
	ds_read_b128 v[168:171], v188 offset:2048
	ds_read_b128 v[172:175], v188 offset:3072
	ds_read_b128 v[176:179], v188 offset:4096
	ds_read_b128 v[180:183], v188 offset:5120
	ds_read_b128 v[184:187], v188 offset:6144
	ds_read_b128 v[188:191], v188 offset:7168
	global_load_lds_dwordx4 v[192:193], off
	v_lshl_add_u64 v[192:193], s[28:29], 0, v[214:215]
	s_add_i32 m0, s38, 0x6000
	s_add_i32 s58, s38, s52
	global_load_lds_dwordx4 v[192:193], off
	v_lshl_add_u64 v[192:193], s[36:37], 0, v[204:205]
	s_mov_b32 m0, s58
	v_lshl_add_u64 v[194:195], s[36:37], 0, v[208:209]
	global_load_lds_dwordx4 v[192:193], off
	s_add_i32 m0, s58, 0x2000
	s_nop 0
	global_load_lds_dwordx4 v[194:195], off
	s_waitcnt vmcnt(10)
	s_waitcnt lgkmcnt(0)
	s_barrier
	s_setprio 1
	s_waitcnt lgkmcnt(0)
	v_mfma_f32_16x16x32_bf16 v[140:143], v[120:123], v[160:163], v[140:143]
	v_mfma_f32_16x16x32_bf16 v[140:143], v[124:127], v[164:167], v[140:143]
	v_mfma_f32_16x16x32_bf16 v[136:139], v[128:131], v[160:163], v[136:139]
	v_mfma_f32_16x16x32_bf16 v[136:139], v[132:135], v[164:167], v[136:139]
	v_mfma_f32_16x16x32_bf16 v[116:119], v[144:147], v[160:163], v[116:119]
	v_mfma_f32_16x16x32_bf16 v[116:119], v[148:151], v[164:167], v[116:119]
	v_mfma_f32_16x16x32_bf16 v[112:115], v[152:155], v[160:163], v[112:115]
	v_mfma_f32_16x16x32_bf16 v[112:115], v[156:159], v[164:167], v[112:115]
	v_mfma_f32_16x16x32_bf16 v[108:111], v[120:123], v[168:171], v[108:111]
	v_mfma_f32_16x16x32_bf16 v[108:111], v[124:127], v[172:175], v[108:111]
	v_mfma_f32_16x16x32_bf16 v[104:107], v[128:131], v[168:171], v[104:107]
	v_mfma_f32_16x16x32_bf16 v[104:107], v[132:135], v[172:175], v[104:107]
	v_mfma_f32_16x16x32_bf16 v[100:103], v[144:147], v[168:171], v[100:103]
	v_mfma_f32_16x16x32_bf16 v[100:103], v[148:151], v[172:175], v[100:103]
	v_mfma_f32_16x16x32_bf16 v[96:99], v[152:155], v[168:171], v[96:99]
	v_mfma_f32_16x16x32_bf16 v[96:99], v[156:159], v[172:175], v[96:99]
	s_setprio 0
	s_setprio 1
	v_mfma_f32_16x16x32_bf16 v[92:95], v[120:123], v[176:179], v[92:95]
	v_mfma_f32_16x16x32_bf16 v[92:95], v[124:127], v[180:183], v[92:95]
	v_mfma_f32_16x16x32_bf16 v[88:91], v[128:131], v[176:179], v[88:91]
	v_mfma_f32_16x16x32_bf16 v[88:91], v[132:135], v[180:183], v[88:91]
	v_mfma_f32_16x16x32_bf16 v[84:87], v[144:147], v[176:179], v[84:87]
	v_mfma_f32_16x16x32_bf16 v[84:87], v[148:151], v[180:183], v[84:87]
	v_mfma_f32_16x16x32_bf16 v[80:83], v[152:155], v[176:179], v[80:83]
	v_mfma_f32_16x16x32_bf16 v[80:83], v[156:159], v[180:183], v[80:83]
	v_mfma_f32_16x16x32_bf16 v[76:79], v[120:123], v[184:187], v[76:79]
	v_mfma_f32_16x16x32_bf16 v[76:79], v[124:127], v[188:191], v[76:79]
	v_mfma_f32_16x16x32_bf16 v[72:75], v[128:131], v[184:187], v[72:75]
	v_mfma_f32_16x16x32_bf16 v[72:75], v[132:135], v[188:191], v[72:75]
	v_mfma_f32_16x16x32_bf16 v[68:71], v[144:147], v[184:187], v[68:71]
	v_mfma_f32_16x16x32_bf16 v[68:71], v[148:151], v[188:191], v[68:71]
	v_mfma_f32_16x16x32_bf16 v[64:67], v[152:155], v[184:187], v[64:67]
	v_mfma_f32_16x16x32_bf16 v[64:67], v[156:159], v[188:191], v[64:67]
	s_setprio 0
	s_barrier
	s_mov_b32 m0, s39
	v_lshl_add_u64 v[196:197], s[30:31], 0, v[206:207]
	s_add_u32 s58, s30, 0x2b0000
	ds_read_b128 v[160:163], v239
	ds_read_b128 v[164:167], v239 offset:1024
	ds_read_b128 v[168:171], v239 offset:2048
	ds_read_b128 v[172:175], v239 offset:3072
	ds_read_b128 v[176:179], v239 offset:4096
	ds_read_b128 v[180:183], v239 offset:5120
	ds_read_b128 v[184:187], v239 offset:6144
	ds_read_b128 v[188:191], v239 offset:7168
	global_load_lds_dwordx4 v[196:197], off
	v_lshl_add_u64 v[198:199], s[30:31], 0, v[210:211]
	s_mov_b32 m0, s40
	s_addc_u32 s59, s31, 0
	global_load_lds_dwordx4 v[198:199], off
	v_lshl_add_u64 v[200:201], s[58:59], 0, v[206:207]
	s_mov_b32 m0, s41
	s_nop 0
	global_load_lds_dwordx4 v[200:201], off
	v_lshl_add_u64 v[200:201], s[58:59], 0, v[210:211]
	s_mov_b32 m0, s42
	s_nop 0
	global_load_lds_dwordx4 v[200:201], off
	s_waitcnt vmcnt(8)
	s_waitcnt lgkmcnt(0)
	s_barrier
; #define PG8_STAGE(bufoff, gbase, voff) do { _Pragma("unroll") for (int _i = 0; _i < 2; ++_i) \
;         __builtin_amdgcn_global_load_lds((const unsigned*)((const char*)(gbase) + (voff)[_i]), (LAS unsigned*)(lds + (bufoff) + ldsw + _i * 8192), 16, 0, 0); } while (0)
; #define PG8_LDA(dst, off) do { _Pragma("unroll") for (int m = 0; m < 4; ++m) _Pragma("unroll") for (int k = 0; k < 2; ++k) dst[m][k] = *(const LAS bf16x8*)(lds + (off) + aoff + m * 2048 + k * 1024); } while (0)
; #define PG8_LDB(dst, b, h) do { _Pragma("unroll") for (int n = 0; n < 2; ++n) _Pragma("unroll") for (int k = 0; k < 2; ++k) dst[n][k] = *(const LAS bf16x8*)(lds + PG8_SB(b, h) + boff + n * 2048 + k * 1024); } while (0)
; #define PG8_MMA(ai, bj, At, Bt) do { __builtin_amdgcn_s_setprio(1); _Pragma("unroll") for (int m = 0; m < 4; ++m) _Pragma("unroll") for (int n = 0; n < 2; ++n) _Pragma("unroll") for (int k = 0; k < 2; ++k) \
;         acc[ai][bj][m][n] = __builtin_amdgcn_mfma_f32_16x16x32_bf16(Bt[n][k], At[m][k], acc[ai][bj][m][n], 0, 0, 0); __builtin_amdgcn_s_setprio(0); } while (0)
; #define PG8_WAIT_V(n) asm volatile("s_waitcnt vmcnt(" #n ")" ::: "memory")
; #define PG8_WAIT_L(n) asm volatile("s_waitcnt lgkmcnt(" #n ")" ::: "memory")
; #define PG8_BAR __builtin_amdgcn_s_barrier()
; #define PG8_SCHED __builtin_amdgcn_sched_barrier(0)
; template <class Epi, bool ALIGN_EPI = true>
; __device__ __forceinline__ void gemm_phase(LAS unsigned char* lds, const Gemm g, const StaticOrder& S, const Epi& E) {
;     ...
;             PG8_WAIT_V(8); PG8_WAIT_L(0); PG8_BAR; PG8_MMA(1, 0, At, B0); PG8_MMA(1, 1, At, B1); PG8_BAR; PG8_SCHED;
;             PG8_LDB(B0, 1, 0); PG8_LDB(B1, 1, 1); PG8_SCHED; PG8_LDA(At, o1); PG8_STAGE(PG8_SA1(0), a2 + hstep, voffA); PG8_STAGE(o0, a3, voffA);
;             PG8_WAIT_V(10); PG8_WAIT_L(0); PG8_BAR; PG8_MMA(0, 0, At, B0); PG8_MMA(0, 1, At, B1); PG8_BAR; PG8_SCHED;
	s_setprio 1
	s_waitcnt lgkmcnt(0)
	v_mfma_f32_16x16x32_bf16 v[60:63], v[120:123], v[160:163], v[60:63]
	v_mfma_f32_16x16x32_bf16 v[60:63], v[124:127], v[164:167], v[60:63]
	v_mfma_f32_16x16x32_bf16 v[56:59], v[128:131], v[160:163], v[56:59]
	v_mfma_f32_16x16x32_bf16 v[56:59], v[132:135], v[164:167], v[56:59]
	v_mfma_f32_16x16x32_bf16 v[52:55], v[144:147], v[160:163], v[52:55]
	v_mfma_f32_16x16x32_bf16 v[52:55], v[148:151], v[164:167], v[52:55]
	v_mfma_f32_16x16x32_bf16 v[48:51], v[152:155], v[160:163], v[48:51]
	v_mfma_f32_16x16x32_bf16 v[48:51], v[156:159], v[164:167], v[48:51]
	v_mfma_f32_16x16x32_bf16 v[44:47], v[120:123], v[168:171], v[44:47]
	v_mfma_f32_16x16x32_bf16 v[44:47], v[124:127], v[172:175], v[44:47]
	v_mfma_f32_16x16x32_bf16 v[40:43], v[128:131], v[168:171], v[40:43]
	v_mfma_f32_16x16x32_bf16 v[40:43], v[132:135], v[172:175], v[40:43]
	v_mfma_f32_16x16x32_bf16 v[36:39], v[144:147], v[168:171], v[36:39]
	v_mfma_f32_16x16x32_bf16 v[36:39], v[148:151], v[172:175], v[36:39]
	v_mfma_f32_16x16x32_bf16 v[32:35], v[152:155], v[168:171], v[32:35]
	v_mfma_f32_16x16x32_bf16 v[32:35], v[156:159], v[172:175], v[32:35]
	s_setprio 0
	s_setprio 1
	v_mfma_f32_16x16x32_bf16 v[28:31], v[120:123], v[176:179], v[28:31]
	v_mfma_f32_16x16x32_bf16 v[28:31], v[124:127], v[180:183], v[28:31]
	v_mfma_f32_16x16x32_bf16 v[24:27], v[128:131], v[176:179], v[24:27]
	v_mfma_f32_16x16x32_bf16 v[24:27], v[132:135], v[180:183], v[24:27]
	v_mfma_f32_16x16x32_bf16 v[20:23], v[144:147], v[176:179], v[20:23]
	v_mfma_f32_16x16x32_bf16 v[20:23], v[148:151], v[180:183], v[20:23]
	v_mfma_f32_16x16x32_bf16 v[16:19], v[152:155], v[176:179], v[16:19]
	v_mfma_f32_16x16x32_bf16 v[16:19], v[156:159], v[180:183], v[16:19]
	v_mfma_f32_16x16x32_bf16 v[12:15], v[120:123], v[184:187], v[12:15]
	v_mfma_f32_16x16x32_bf16 v[12:15], v[124:127], v[188:191], v[12:15]
	v_mfma_f32_16x16x32_bf16 v[8:11], v[128:131], v[184:187], v[8:11]
	v_mfma_f32_16x16x32_bf16 v[8:11], v[132:135], v[188:191], v[8:11]
	v_mfma_f32_16x16x32_bf16 v[4:7], v[144:147], v[184:187], v[4:7]
	v_mfma_f32_16x16x32_bf16 v[4:7], v[148:151], v[188:191], v[4:7]
	v_mfma_f32_16x16x32_bf16 v[0:3], v[152:155], v[184:187], v[0:3]
	v_mfma_f32_16x16x32_bf16 v[0:3], v[156:159], v[188:191], v[0:3]
	s_setprio 0
	s_barrier
	s_add_i32 s58, 0, 0x10000
	s_add_i32 s59, 0, 0x14000
	v_add_u32_e32 v132, s58, v238
	v_add_u32_e32 v156, s59, v238
	ds_read_b128 v[120:123], v132
	ds_read_b128 v[124:127], v132 offset:1024
	ds_read_b128 v[128:131], v132 offset:2048
	ds_read_b128 v[132:135], v132 offset:3072
	ds_read_b128 v[144:147], v156
	ds_read_b128 v[148:151], v156 offset:1024
	ds_read_b128 v[152:155], v156 offset:2048
	ds_read_b128 v[156:159], v156 offset:3072
	s_add_u32 s36, s36, 0x2b0000
	s_addc_u32 s37, s37, 0
	s_mov_b32 m0, s38
	v_add_u32_e32 v188, s49, v239
	v_lshl_add_u64 v[200:201], s[36:37], 0, v[204:205]
	ds_read_b128 v[160:163], v188
	ds_read_b128 v[164:167], v188 offset:1024
	ds_read_b128 v[168:171], v188 offset:2048
	ds_read_b128 v[172:175], v188 offset:3072
	ds_read_b128 v[176:179], v188 offset:4096
	ds_read_b128 v[180:183], v188 offset:5120
	ds_read_b128 v[184:187], v188 offset:6144
	ds_read_b128 v[188:191], v188 offset:7168
	global_load_lds_dwordx4 v[200:201], off
	v_lshl_add_u64 v[200:201], s[36:37], 0, v[208:209]
	s_mov_b32 m0, s43
	s_add_i32 s36, s38, s47
	global_load_lds_dwordx4 v[200:201], off
	v_lshl_add_u64 v[192:193], v[192:193], 0, s[8:9]
	s_mov_b32 m0, s36
	s_nop 0
	global_load_lds_dwordx4 v[192:193], off
	v_lshl_add_u64 v[192:193], v[194:195], 0, s[8:9]
	s_add_i32 m0, s36, 0x2000
	s_nop 0
	global_load_lds_dwordx4 v[192:193], off
	s_waitcnt vmcnt(10)
	s_waitcnt lgkmcnt(0)
	s_barrier
; #define PG8_STAGE(bufoff, gbase, voff) do { _Pragma("unroll") for (int _i = 0; _i < 2; ++_i) \
;         __builtin_amdgcn_global_load_lds((const unsigned*)((const char*)(gbase) + (voff)[_i]), (LAS unsigned*)(lds + (bufoff) + ldsw + _i * 8192), 16, 0, 0); } while (0)
; #define PG8_LDA(dst, off) do { _Pragma("unroll") for (int m = 0; m < 4; ++m) _Pragma("unroll") for (int k = 0; k < 2; ++k) dst[m][k] = *(const LAS bf16x8*)(lds + (off) + aoff + m * 2048 + k * 1024); } while (0)
; #define PG8_MMA(ai, bj, At, Bt) do { __builtin_amdgcn_s_setprio(1); _Pragma("unroll") for (int m = 0; m < 4; ++m) _Pragma("unroll") for (int n = 0; n < 2; ++n) _Pragma("unroll") for (int k = 0; k < 2; ++k) \
;         acc[ai][bj][m][n] = __builtin_amdgcn_mfma_f32_16x16x32_bf16(Bt[n][k], At[m][k], acc[ai][bj][m][n], 0, 0, 0); __builtin_amdgcn_s_setprio(0); } while (0)
; #define PG8_WAIT_V(n) asm volatile("s_waitcnt vmcnt(" #n ")" ::: "memory")
; #define PG8_WAIT_L(n) asm volatile("s_waitcnt lgkmcnt(" #n ")" ::: "memory")
; #define PG8_BAR __builtin_amdgcn_s_barrier()
; #define PG8_SCHED __builtin_amdgcn_sched_barrier(0)
; template <class Epi, bool ALIGN_EPI = true>
; __device__ __forceinline__ void gemm_phase(LAS unsigned char* lds, const Gemm g, const StaticOrder& S, const Epi& E) {
;     ...
;             PG8_WAIT_V(10); PG8_WAIT_L(0); PG8_BAR; PG8_MMA(0, 0, At, B0); PG8_MMA(0, 1, At, B1); PG8_BAR; PG8_SCHED;
;             PG8_LDA(At, PG8_SA1(1)); PG8_STAGE(PG8_SB(1, 0), b3, voffB); PG8_STAGE(PG8_SB(1, 1), b3 + hstep, voffB);
;             PG8_WAIT_V(8); PG8_WAIT_L(0); PG8_BAR; PG8_MMA(1, 0, At, B0); PG8_MMA(1, 1, At, B1); PG8_BAR; PG8_SCHED;
;             { const int t_ = o0; o0 = o2; o2 = o1; o1 = t_; }
;         }
;         if constexpr (ALIGN_EPI) { if (wr == 0) PG8_BAR; }
	s_setprio 1
	s_waitcnt lgkmcnt(0)
	v_mfma_f32_16x16x32_bf16 v[140:143], v[120:123], v[160:163], v[140:143]
	v_mfma_f32_16x16x32_bf16 v[140:143], v[124:127], v[164:167], v[140:143]
	v_mfma_f32_16x16x32_bf16 v[136:139], v[128:131], v[160:163], v[136:139]
	v_mfma_f32_16x16x32_bf16 v[136:139], v[132:135], v[164:167], v[136:139]
	v_mfma_f32_16x16x32_bf16 v[116:119], v[144:147], v[160:163], v[116:119]
	v_mfma_f32_16x16x32_bf16 v[116:119], v[148:151], v[164:167], v[116:119]
	v_mfma_f32_16x16x32_bf16 v[112:115], v[152:155], v[160:163], v[112:115]
	v_mfma_f32_16x16x32_bf16 v[112:115], v[156:159], v[164:167], v[112:115]
	v_mfma_f32_16x16x32_bf16 v[108:111], v[120:123], v[168:171], v[108:111]
	v_mfma_f32_16x16x32_bf16 v[108:111], v[124:127], v[172:175], v[108:111]
	v_mfma_f32_16x16x32_bf16 v[104:107], v[128:131], v[168:171], v[104:107]
	v_mfma_f32_16x16x32_bf16 v[104:107], v[132:135], v[172:175], v[104:107]
	v_mfma_f32_16x16x32_bf16 v[100:103], v[144:147], v[168:171], v[100:103]
	v_mfma_f32_16x16x32_bf16 v[100:103], v[148:151], v[172:175], v[100:103]
	v_mfma_f32_16x16x32_bf16 v[96:99], v[152:155], v[168:171], v[96:99]
	v_mfma_f32_16x16x32_bf16 v[96:99], v[156:159], v[172:175], v[96:99]
	s_setprio 0
	s_setprio 1
	v_mfma_f32_16x16x32_bf16 v[92:95], v[120:123], v[176:179], v[92:95]
	v_mfma_f32_16x16x32_bf16 v[92:95], v[124:127], v[180:183], v[92:95]
	v_mfma_f32_16x16x32_bf16 v[88:91], v[128:131], v[176:179], v[88:91]
	v_mfma_f32_16x16x32_bf16 v[88:91], v[132:135], v[180:183], v[88:91]
	v_mfma_f32_16x16x32_bf16 v[84:87], v[144:147], v[176:179], v[84:87]
	v_mfma_f32_16x16x32_bf16 v[84:87], v[148:151], v[180:183], v[84:87]
	v_mfma_f32_16x16x32_bf16 v[80:83], v[152:155], v[176:179], v[80:83]
	v_mfma_f32_16x16x32_bf16 v[80:83], v[156:159], v[180:183], v[80:83]
	v_mfma_f32_16x16x32_bf16 v[76:79], v[120:123], v[184:187], v[76:79]
	v_mfma_f32_16x16x32_bf16 v[76:79], v[124:127], v[188:191], v[76:79]
	v_mfma_f32_16x16x32_bf16 v[72:75], v[128:131], v[184:187], v[72:75]
	v_mfma_f32_16x16x32_bf16 v[72:75], v[132:135], v[188:191], v[72:75]
	v_mfma_f32_16x16x32_bf16 v[68:71], v[144:147], v[184:187], v[68:71]
	v_mfma_f32_16x16x32_bf16 v[68:71], v[148:151], v[188:191], v[68:71]
	v_mfma_f32_16x16x32_bf16 v[64:67], v[152:155], v[184:187], v[64:67]
	v_mfma_f32_16x16x32_bf16 v[64:67], v[156:159], v[188:191], v[64:67]
	s_setprio 0
	s_barrier
	s_add_i32 s36, s58, s35
	v_lshl_add_u64 v[192:193], v[196:197], 0, s[8:9]
	s_mov_b32 m0, s36
	ds_read_b128 v[160:163], v239 offset:16384
	ds_read_b128 v[164:167], v239 offset:17408
	ds_read_b128 v[168:171], v239 offset:18432
	ds_read_b128 v[172:175], v239 offset:19456
	ds_read_b128 v[176:179], v239 offset:20480
	ds_read_b128 v[180:183], v239 offset:21504
	ds_read_b128 v[184:187], v239 offset:22528
	ds_read_b128 v[188:191], v239 offset:23552
	global_load_lds_dwordx4 v[192:193], off
	s_add_i32 m0, s36, 0x2000
	s_add_u32 s30, s30, 0x2b0080
	v_lshl_add_u64 v[192:193], v[198:199], 0, s[8:9]
	s_addc_u32 s31, s31, 0
	s_add_i32 s36, s59, s35
	global_load_lds_dwordx4 v[192:193], off
	v_lshl_add_u64 v[192:193], s[30:31], 0, v[206:207]
	s_mov_b32 m0, s36
	s_nop 0
	global_load_lds_dwordx4 v[192:193], off
	v_lshl_add_u64 v[192:193], s[30:31], 0, v[210:211]
	s_add_i32 m0, s36, 0x2000
	s_nop 0
	global_load_lds_dwordx4 v[192:193], off
	s_waitcnt vmcnt(8)
	s_waitcnt lgkmcnt(0)
	s_barrier
	s_setprio 1
	s_waitcnt lgkmcnt(0)
	v_mfma_f32_16x16x32_bf16 v[60:63], v[120:123], v[160:163], v[60:63]
	v_mfma_f32_16x16x32_bf16 v[60:63], v[124:127], v[164:167], v[60:63]
	v_mfma_f32_16x16x32_bf16 v[56:59], v[128:131], v[160:163], v[56:59]
	v_mfma_f32_16x16x32_bf16 v[56:59], v[132:135], v[164:167], v[56:59]
	v_mfma_f32_16x16x32_bf16 v[52:55], v[144:147], v[160:163], v[52:55]
	v_mfma_f32_16x16x32_bf16 v[52:55], v[148:151], v[164:167], v[52:55]
	v_mfma_f32_16x16x32_bf16 v[48:51], v[152:155], v[160:163], v[48:51]
	v_mfma_f32_16x16x32_bf16 v[48:51], v[156:159], v[164:167], v[48:51]
	v_mfma_f32_16x16x32_bf16 v[44:47], v[120:123], v[168:171], v[44:47]
	v_mfma_f32_16x16x32_bf16 v[44:47], v[124:127], v[172:175], v[44:47]
	v_mfma_f32_16x16x32_bf16 v[40:43], v[128:131], v[168:171], v[40:43]
	v_mfma_f32_16x16x32_bf16 v[40:43], v[132:135], v[172:175], v[40:43]
	v_mfma_f32_16x16x32_bf16 v[36:39], v[144:147], v[168:171], v[36:39]
	v_mfma_f32_16x16x32_bf16 v[36:39], v[148:151], v[172:175], v[36:39]
	v_mfma_f32_16x16x32_bf16 v[32:35], v[152:155], v[168:171], v[32:35]
	v_mfma_f32_16x16x32_bf16 v[32:35], v[156:159], v[172:175], v[32:35]
	s_setprio 0
	s_setprio 1
	v_mfma_f32_16x16x32_bf16 v[28:31], v[120:123], v[176:179], v[28:31]
	v_mfma_f32_16x16x32_bf16 v[28:31], v[124:127], v[180:183], v[28:31]
	v_mfma_f32_16x16x32_bf16 v[24:27], v[128:131], v[176:179], v[24:27]
	v_mfma_f32_16x16x32_bf16 v[24:27], v[132:135], v[180:183], v[24:27]
	v_mfma_f32_16x16x32_bf16 v[20:23], v[144:147], v[176:179], v[20:23]
	v_mfma_f32_16x16x32_bf16 v[20:23], v[148:151], v[180:183], v[20:23]
	v_mfma_f32_16x16x32_bf16 v[16:19], v[152:155], v[176:179], v[16:19]
	v_mfma_f32_16x16x32_bf16 v[16:19], v[156:159], v[180:183], v[16:19]
	v_mfma_f32_16x16x32_bf16 v[12:15], v[120:123], v[184:187], v[12:15]
	v_mfma_f32_16x16x32_bf16 v[12:15], v[124:127], v[188:191], v[12:15]
	v_mfma_f32_16x16x32_bf16 v[8:11], v[128:131], v[184:187], v[8:11]
	v_mfma_f32_16x16x32_bf16 v[8:11], v[132:135], v[188:191], v[8:11]
	v_mfma_f32_16x16x32_bf16 v[4:7], v[144:147], v[184:187], v[4:7]
	v_mfma_f32_16x16x32_bf16 v[4:7], v[148:151], v[188:191], v[4:7]
	v_mfma_f32_16x16x32_bf16 v[0:3], v[152:155], v[184:187], v[0:3]
	v_mfma_f32_16x16x32_bf16 v[0:3], v[156:159], v[188:191], v[0:3]
	s_setprio 0
	s_barrier
	s_add_i32 s57, s57, 2
	s_add_u32 s28, s28, 0x100
	s_addc_u32 s29, s29, 0
	s_add_u32 s55, s55, 0x100
	s_addc_u32 s56, s56, 0
	s_cmpk_gt_u32 s57, 0xa9
	s_mov_b32 s30, s52
	s_cbranch_scc0 .LBB0_1077
	s_and_b64 vcc, exec, s[10:11]
	s_cbranch_vccz .LBB0_1080
	s_barrier
